# hoisted ss loads in SwiGLU+in-proj epilogues, barrier XGEN-before-inv, removed vmcnt0 in FFN1-up loop
# speedup vs baseline: 1.0151x; 1.0151x over previous
.LBB0_100:
	s_or_b64 exec, exec, s[8:9]
	buffer_inv sc1
	s_waitcnt vmcnt(0)

.LBB0_111:
	s_add_u32 s28, s26, 0xfffc0080
	s_addc_u32 s29, s27, -1
	s_add_i32 s57, 0, 0x10000
	s_cmp_eq_u32 s56, 12
	s_cselect_b32 s31, s19, s29
	s_cselect_b32 s30, s52, s28
	v_add_u32_e32 v150, s57, v1
	s_cselect_b32 s29, s17, s55
	s_cselect_b32 s28, s53, s54
	s_add_i32 s60, 0, 0x14000
	ds_read_b128 v[142:145], v150
	ds_read_b128 v[146:149], v150 offset:1024
	ds_read_b128 v[154:157], v150 offset:2048
	ds_read_b128 v[158:161], v150 offset:3072
	v_add_u32_e32 v150, s60, v1
	s_nop 0
	ds_read_b128 v[162:165], v150
	ds_read_b128 v[166:169], v150 offset:1024
	ds_read_b128 v[170:173], v150 offset:2048
	ds_read_b128 v[174:177], v150 offset:3072
	v_lshl_add_u64 v[150:151], s[26:27], 0, v[138:139]
	s_add_i32 m0, s43, 0xc000
	ds_read_b128 v[178:181], v152
	ds_read_b128 v[182:185], v152 offset:1024
	ds_read_b128 v[186:189], v152 offset:2048
	ds_read_b128 v[190:193], v152 offset:3072
	ds_read_b128 v[204:207], v152 offset:4096
	ds_read_b128 v[208:211], v152 offset:5120
	ds_read_b128 v[212:215], v152 offset:6144
	ds_read_b128 v[228:231], v152 offset:7168
	global_load_lds_dwordx4 v[150:151], off
	v_lshl_add_u64 v[150:151], s[26:27], 0, v[140:141]
	s_add_i32 m0, s43, 0xe000
	s_nop 0
	global_load_lds_dwordx4 v[150:151], off
	s_waitcnt vmcnt(8)
	s_waitcnt lgkmcnt(0)
	s_barrier
	s_setprio 1
	s_waitcnt lgkmcnt(0)
	v_mfma_f32_16x16x32_bf16 v[126:129], v[142:145], v[178:181], v[126:129]
	v_mfma_f32_16x16x32_bf16 v[122:125], v[154:157], v[178:181], v[122:125]
	v_mfma_f32_16x16x32_bf16 v[110:113], v[142:145], v[186:189], v[110:113]
	v_mfma_f32_16x16x32_bf16 v[106:109], v[154:157], v[186:189], v[106:109]
	v_mfma_f32_16x16x32_bf16 v[94:97], v[142:145], v[204:207], v[94:97]
	v_mfma_f32_16x16x32_bf16 v[90:93], v[154:157], v[204:207], v[90:93]
	v_mfma_f32_16x16x32_bf16 v[78:81], v[142:145], v[212:215], v[78:81]
	v_mfma_f32_16x16x32_bf16 v[74:77], v[154:157], v[212:215], v[74:77]
	v_mfma_f32_16x16x32_bf16 v[126:129], v[146:149], v[182:185], v[126:129]
	v_mfma_f32_16x16x32_bf16 v[122:125], v[158:161], v[182:185], v[122:125]
	v_mfma_f32_16x16x32_bf16 v[110:113], v[146:149], v[190:193], v[110:113]
	v_mfma_f32_16x16x32_bf16 v[106:109], v[158:161], v[190:193], v[106:109]
	v_mfma_f32_16x16x32_bf16 v[94:97], v[146:149], v[208:211], v[94:97]
	v_mfma_f32_16x16x32_bf16 v[90:93], v[158:161], v[208:211], v[90:93]
	v_mfma_f32_16x16x32_bf16 v[78:81], v[146:149], v[228:231], v[78:81]
	v_mfma_f32_16x16x32_bf16 v[74:77], v[158:161], v[228:231], v[74:77]
	s_setprio 0
	s_setprio 1
	v_mfma_f32_16x16x32_bf16 v[118:121], v[162:165], v[178:181], v[118:121]
	v_mfma_f32_16x16x32_bf16 v[114:117], v[170:173], v[178:181], v[114:117]
	v_mfma_f32_16x16x32_bf16 v[102:105], v[162:165], v[186:189], v[102:105]
	v_mfma_f32_16x16x32_bf16 v[98:101], v[170:173], v[186:189], v[98:101]
	v_mfma_f32_16x16x32_bf16 v[86:89], v[162:165], v[204:207], v[86:89]
	v_mfma_f32_16x16x32_bf16 v[82:85], v[170:173], v[204:207], v[82:85]
	v_mfma_f32_16x16x32_bf16 v[70:73], v[162:165], v[212:215], v[70:73]
	v_mfma_f32_16x16x32_bf16 v[66:69], v[170:173], v[212:215], v[66:69]
	v_mfma_f32_16x16x32_bf16 v[118:121], v[166:169], v[182:185], v[118:121]
	v_mfma_f32_16x16x32_bf16 v[114:117], v[174:177], v[182:185], v[114:117]
	v_mfma_f32_16x16x32_bf16 v[102:105], v[166:169], v[190:193], v[102:105]
	v_mfma_f32_16x16x32_bf16 v[98:101], v[174:177], v[190:193], v[98:101]
	v_mfma_f32_16x16x32_bf16 v[86:89], v[166:169], v[208:211], v[86:89]
	v_mfma_f32_16x16x32_bf16 v[82:85], v[174:177], v[208:211], v[82:85]
	v_mfma_f32_16x16x32_bf16 v[70:73], v[166:169], v[228:231], v[70:73]
	v_mfma_f32_16x16x32_bf16 v[66:69], v[174:177], v[228:231], v[66:69]
	s_setprio 0
	s_barrier
	s_add_i32 s57, s57, s42
	v_lshl_add_u64 v[150:151], s[28:29], 0, v[134:135]
	s_mov_b32 m0, s57
	ds_read_b128 v[178:181], v152 offset:16384
	ds_read_b128 v[182:185], v152 offset:17408
	ds_read_b128 v[186:189], v152 offset:18432
	ds_read_b128 v[190:193], v152 offset:19456
	ds_read_b128 v[204:207], v152 offset:20480
	ds_read_b128 v[208:211], v152 offset:21504
	ds_read_b128 v[212:215], v152 offset:22528
	ds_read_b128 v[228:231], v152 offset:23552
	global_load_lds_dwordx4 v[150:151], off
	s_add_i32 m0, s57, 0x2000
	s_add_u32 s58, s28, 0x40000
	v_lshl_add_u64 v[194:195], s[28:29], 0, v[130:131]
	s_addc_u32 s59, s29, 0
	s_add_i32 s57, s60, s42
	global_load_lds_dwordx4 v[194:195], off
	v_lshl_add_u64 v[216:217], s[58:59], 0, v[134:135]
	s_mov_b32 m0, s57
	v_lshl_add_u64 v[232:233], s[30:31], 0, v[132:133]
	global_load_lds_dwordx4 v[216:217], off
	v_lshl_add_u64 v[216:217], s[58:59], 0, v[130:131]
	s_add_i32 m0, s57, 0x2000
	s_nop 0
	global_load_lds_dwordx4 v[216:217], off
	v_lshl_add_u64 v[216:217], s[30:31], 0, v[136:137]
	s_mov_b32 m0, s43
	s_nop 0
	global_load_lds_dwordx4 v[216:217], off
	s_mov_b32 m0, s44
	s_nop 0
	global_load_lds_dwordx4 v[232:233], off
	s_waitcnt vmcnt(8)
	s_waitcnt lgkmcnt(0)
	s_barrier
	s_setprio 1
	s_waitcnt lgkmcnt(0)
	v_mfma_f32_16x16x32_bf16 v[62:65], v[142:145], v[178:181], v[62:65]
	v_mfma_f32_16x16x32_bf16 v[58:61], v[154:157], v[178:181], v[58:61]
	v_mfma_f32_16x16x32_bf16 v[46:49], v[142:145], v[186:189], v[46:49]
	v_mfma_f32_16x16x32_bf16 v[42:45], v[154:157], v[186:189], v[42:45]
	v_mfma_f32_16x16x32_bf16 v[30:33], v[142:145], v[204:207], v[30:33]
	v_mfma_f32_16x16x32_bf16 v[26:29], v[154:157], v[204:207], v[26:29]
	v_mfma_f32_16x16x32_bf16 v[14:17], v[142:145], v[212:215], v[14:17]
	v_mfma_f32_16x16x32_bf16 v[10:13], v[154:157], v[212:215], v[10:13]
	v_mfma_f32_16x16x32_bf16 v[62:65], v[146:149], v[182:185], v[62:65]
	v_mfma_f32_16x16x32_bf16 v[58:61], v[158:161], v[182:185], v[58:61]
	v_mfma_f32_16x16x32_bf16 v[46:49], v[146:149], v[190:193], v[46:49]
	v_mfma_f32_16x16x32_bf16 v[42:45], v[158:161], v[190:193], v[42:45]
	v_mfma_f32_16x16x32_bf16 v[30:33], v[146:149], v[208:211], v[30:33]
	v_mfma_f32_16x16x32_bf16 v[26:29], v[158:161], v[208:211], v[26:29]
	v_mfma_f32_16x16x32_bf16 v[14:17], v[146:149], v[228:231], v[14:17]
	v_mfma_f32_16x16x32_bf16 v[10:13], v[158:161], v[228:231], v[10:13]
	s_setprio 0
	s_setprio 1
	v_mfma_f32_16x16x32_bf16 v[54:57], v[162:165], v[178:181], v[54:57]
	v_mfma_f32_16x16x32_bf16 v[50:53], v[170:173], v[178:181], v[50:53]
	v_mfma_f32_16x16x32_bf16 v[38:41], v[162:165], v[186:189], v[38:41]
	v_mfma_f32_16x16x32_bf16 v[34:37], v[170:173], v[186:189], v[34:37]
	v_mfma_f32_16x16x32_bf16 v[22:25], v[162:165], v[204:207], v[22:25]
	v_mfma_f32_16x16x32_bf16 v[18:21], v[170:173], v[204:207], v[18:21]
	v_mfma_f32_16x16x32_bf16 v[6:9], v[162:165], v[212:215], v[6:9]
	v_mfma_f32_16x16x32_bf16 v[2:5], v[170:173], v[212:215], v[2:5]
	v_mfma_f32_16x16x32_bf16 v[54:57], v[166:169], v[182:185], v[54:57]
	v_mfma_f32_16x16x32_bf16 v[50:53], v[174:177], v[182:185], v[50:53]
	v_mfma_f32_16x16x32_bf16 v[38:41], v[166:169], v[190:193], v[38:41]
	v_mfma_f32_16x16x32_bf16 v[34:37], v[174:177], v[190:193], v[34:37]
	v_mfma_f32_16x16x32_bf16 v[22:25], v[166:169], v[208:211], v[22:25]
	v_mfma_f32_16x16x32_bf16 v[18:21], v[174:177], v[208:211], v[18:21]
	v_mfma_f32_16x16x32_bf16 v[6:9], v[166:169], v[228:231], v[6:9]
	v_mfma_f32_16x16x32_bf16 v[2:5], v[174:177], v[228:231], v[2:5]
	s_setprio 0
	s_barrier
	s_add_i32 s57, 0, 0x18000
	v_add_u32_e32 v153, s57, v1
	s_add_i32 s58, 0, 0x1c000
	ds_read_b128 v[142:145], v153
	ds_read_b128 v[146:149], v153 offset:1024
	ds_read_b128 v[154:157], v153 offset:2048
	ds_read_b128 v[158:161], v153 offset:3072
	v_add_u32_e32 v153, s58, v1
	ds_read_b128 v[162:165], v153
	ds_read_b128 v[166:169], v153 offset:1024
	ds_read_b128 v[170:173], v153 offset:2048
	ds_read_b128 v[174:177], v153 offset:3072
	s_add_u32 s30, s30, 0x40000
	s_addc_u32 s31, s31, 0
	s_mov_b32 m0, s45
	v_lshl_add_u64 v[234:235], s[30:31], 0, v[136:137]
	ds_read_b128 v[178:181], v152 offset:32768
	ds_read_b128 v[182:185], v152 offset:33792
	ds_read_b128 v[186:189], v152 offset:34816
	ds_read_b128 v[190:193], v152 offset:35840
	ds_read_b128 v[204:207], v152 offset:36864
	ds_read_b128 v[208:211], v152 offset:37888
	ds_read_b128 v[212:215], v152 offset:38912
	ds_read_b128 v[228:231], v152 offset:39936
	global_load_lds_dwordx4 v[234:235], off
	v_lshl_add_u64 v[234:235], s[30:31], 0, v[132:133]
	s_mov_b32 m0, s46
	s_nop 0
	global_load_lds_dwordx4 v[234:235], off
	s_waitcnt vmcnt(8)
	s_waitcnt lgkmcnt(0)
	s_barrier
	s_setprio 1
	s_waitcnt lgkmcnt(0)
	v_mfma_f32_16x16x32_bf16 v[126:129], v[142:145], v[178:181], v[126:129]
	v_mfma_f32_16x16x32_bf16 v[122:125], v[154:157], v[178:181], v[122:125]
	v_mfma_f32_16x16x32_bf16 v[110:113], v[142:145], v[186:189], v[110:113]
	v_mfma_f32_16x16x32_bf16 v[106:109], v[154:157], v[186:189], v[106:109]
	v_mfma_f32_16x16x32_bf16 v[94:97], v[142:145], v[204:207], v[94:97]
	v_mfma_f32_16x16x32_bf16 v[90:93], v[154:157], v[204:207], v[90:93]
	v_mfma_f32_16x16x32_bf16 v[78:81], v[142:145], v[212:215], v[78:81]
	v_mfma_f32_16x16x32_bf16 v[74:77], v[154:157], v[212:215], v[74:77]
	v_mfma_f32_16x16x32_bf16 v[126:129], v[146:149], v[182:185], v[126:129]
	v_mfma_f32_16x16x32_bf16 v[122:125], v[158:161], v[182:185], v[122:125]
	v_mfma_f32_16x16x32_bf16 v[110:113], v[146:149], v[190:193], v[110:113]
	v_mfma_f32_16x16x32_bf16 v[106:109], v[158:161], v[190:193], v[106:109]
	v_mfma_f32_16x16x32_bf16 v[94:97], v[146:149], v[208:211], v[94:97]
	v_mfma_f32_16x16x32_bf16 v[90:93], v[158:161], v[208:211], v[90:93]
	v_mfma_f32_16x16x32_bf16 v[78:81], v[146:149], v[228:231], v[78:81]
	v_mfma_f32_16x16x32_bf16 v[74:77], v[158:161], v[228:231], v[74:77]
	s_setprio 0
	s_setprio 1
	v_mfma_f32_16x16x32_bf16 v[118:121], v[162:165], v[178:181], v[118:121]
	v_mfma_f32_16x16x32_bf16 v[114:117], v[170:173], v[178:181], v[114:117]
	v_mfma_f32_16x16x32_bf16 v[102:105], v[162:165], v[186:189], v[102:105]
	v_mfma_f32_16x16x32_bf16 v[98:101], v[170:173], v[186:189], v[98:101]
	v_mfma_f32_16x16x32_bf16 v[86:89], v[162:165], v[204:207], v[86:89]
	v_mfma_f32_16x16x32_bf16 v[82:85], v[170:173], v[204:207], v[82:85]
	v_mfma_f32_16x16x32_bf16 v[70:73], v[162:165], v[212:215], v[70:73]
	v_mfma_f32_16x16x32_bf16 v[66:69], v[170:173], v[212:215], v[66:69]
	v_mfma_f32_16x16x32_bf16 v[118:121], v[166:169], v[182:185], v[118:121]
	v_mfma_f32_16x16x32_bf16 v[114:117], v[174:177], v[182:185], v[114:117]
	v_mfma_f32_16x16x32_bf16 v[102:105], v[166:169], v[190:193], v[102:105]
	v_mfma_f32_16x16x32_bf16 v[98:101], v[174:177], v[190:193], v[98:101]
	v_mfma_f32_16x16x32_bf16 v[86:89], v[166:169], v[208:211], v[86:89]
	v_mfma_f32_16x16x32_bf16 v[82:85], v[174:177], v[208:211], v[82:85]
	v_mfma_f32_16x16x32_bf16 v[70:73], v[166:169], v[228:231], v[70:73]
	v_mfma_f32_16x16x32_bf16 v[66:69], v[174:177], v[228:231], v[66:69]
	s_setprio 0
	s_barrier
	s_add_i32 s30, s57, s42
	v_lshl_add_u64 v[150:151], v[150:151], 0, s[94:95]
	s_mov_b32 m0, s30
	ds_read_b128 v[178:181], v152 offset:49152
	ds_read_b128 v[182:185], v152 offset:50176
	ds_read_b128 v[186:189], v152 offset:51200
	ds_read_b128 v[190:193], v152 offset:52224
	ds_read_b128 v[204:207], v152 offset:53248
	ds_read_b128 v[208:211], v152 offset:54272
	ds_read_b128 v[212:215], v152 offset:55296
	ds_read_b128 v[228:231], v152 offset:56320
	global_load_lds_dwordx4 v[150:151], off
	s_add_i32 m0, s30, 0x2000
	s_add_u32 s28, s28, 0x40080
	v_lshl_add_u64 v[150:151], v[194:195], 0, s[94:95]
	s_addc_u32 s29, s29, 0
	s_add_i32 s30, s58, s42
	global_load_lds_dwordx4 v[150:151], off
	v_lshl_add_u64 v[150:151], s[28:29], 0, v[134:135]
	s_mov_b32 m0, s30
	s_nop 0
	global_load_lds_dwordx4 v[150:151], off
	v_lshl_add_u64 v[150:151], s[28:29], 0, v[130:131]
	s_add_i32 m0, s30, 0x2000
	s_nop 0
	global_load_lds_dwordx4 v[150:151], off
	v_lshl_add_u64 v[150:151], v[216:217], 0, s[94:95]
	s_mov_b32 m0, s49
	s_nop 0
	global_load_lds_dwordx4 v[150:151], off
	v_lshl_add_u64 v[150:151], v[232:233], 0, s[94:95]
	s_mov_b32 m0, s50
	s_nop 0
	global_load_lds_dwordx4 v[150:151], off
	s_waitcnt vmcnt(8)
	s_waitcnt lgkmcnt(0)
	s_barrier
	s_setprio 1
	s_waitcnt lgkmcnt(0)
	v_mfma_f32_16x16x32_bf16 v[62:65], v[142:145], v[178:181], v[62:65]
	v_mfma_f32_16x16x32_bf16 v[58:61], v[154:157], v[178:181], v[58:61]
	v_mfma_f32_16x16x32_bf16 v[46:49], v[142:145], v[186:189], v[46:49]
	v_mfma_f32_16x16x32_bf16 v[42:45], v[154:157], v[186:189], v[42:45]
	v_mfma_f32_16x16x32_bf16 v[30:33], v[142:145], v[204:207], v[30:33]
	v_mfma_f32_16x16x32_bf16 v[26:29], v[154:157], v[204:207], v[26:29]
	v_mfma_f32_16x16x32_bf16 v[14:17], v[142:145], v[212:215], v[14:17]
	v_mfma_f32_16x16x32_bf16 v[10:13], v[154:157], v[212:215], v[10:13]
	v_mfma_f32_16x16x32_bf16 v[62:65], v[146:149], v[182:185], v[62:65]
	v_mfma_f32_16x16x32_bf16 v[58:61], v[158:161], v[182:185], v[58:61]
	v_mfma_f32_16x16x32_bf16 v[46:49], v[146:149], v[190:193], v[46:49]
	v_mfma_f32_16x16x32_bf16 v[42:45], v[158:161], v[190:193], v[42:45]
	v_mfma_f32_16x16x32_bf16 v[30:33], v[146:149], v[208:211], v[30:33]
	v_mfma_f32_16x16x32_bf16 v[26:29], v[158:161], v[208:211], v[26:29]
	v_mfma_f32_16x16x32_bf16 v[14:17], v[146:149], v[228:231], v[14:17]
	v_mfma_f32_16x16x32_bf16 v[10:13], v[158:161], v[228:231], v[10:13]
	s_setprio 0
	s_setprio 1
	v_mfma_f32_16x16x32_bf16 v[54:57], v[162:165], v[178:181], v[54:57]
	v_mfma_f32_16x16x32_bf16 v[50:53], v[170:173], v[178:181], v[50:53]
	v_mfma_f32_16x16x32_bf16 v[38:41], v[162:165], v[186:189], v[38:41]
	v_mfma_f32_16x16x32_bf16 v[34:37], v[170:173], v[186:189], v[34:37]
	v_mfma_f32_16x16x32_bf16 v[22:25], v[162:165], v[204:207], v[22:25]
	v_mfma_f32_16x16x32_bf16 v[18:21], v[170:173], v[204:207], v[18:21]
	v_mfma_f32_16x16x32_bf16 v[6:9], v[162:165], v[212:215], v[6:9]
	v_mfma_f32_16x16x32_bf16 v[2:5], v[170:173], v[212:215], v[2:5]
	v_mfma_f32_16x16x32_bf16 v[54:57], v[166:169], v[182:185], v[54:57]
	v_mfma_f32_16x16x32_bf16 v[50:53], v[174:177], v[182:185], v[50:53]
	v_mfma_f32_16x16x32_bf16 v[38:41], v[166:169], v[190:193], v[38:41]
	v_mfma_f32_16x16x32_bf16 v[34:37], v[174:177], v[190:193], v[34:37]
	v_mfma_f32_16x16x32_bf16 v[22:25], v[166:169], v[208:211], v[22:25]
	v_mfma_f32_16x16x32_bf16 v[18:21], v[174:177], v[208:211], v[18:21]
	v_mfma_f32_16x16x32_bf16 v[6:9], v[166:169], v[228:231], v[6:9]
	v_mfma_f32_16x16x32_bf16 v[2:5], v[174:177], v[228:231], v[2:5]
	s_setprio 0
	s_barrier
	s_add_i32 s56, s56, 2
	s_add_u32 s26, s26, 0x100
	s_addc_u32 s27, s27, 0
	s_add_u32 s54, s54, 0x100
	s_addc_u32 s55, s55, 0
	s_cmp_gt_u32 s56, 13
	s_cbranch_scc0 .LBB0_111
	s_and_b64 vcc, exec, s[14:15]
	s_cbranch_vccz .LBB0_114
	s_barrier
.LBB0_114:
	v_mov_b32_e32 v143, v218
	s_lshl_b32 s17, s24, 8
	s_add_i32 s17, s17, s47
	v_and_or_b32 v142, v143, 15, s17
	s_lshl_b32 s17, s25, 7
	v_lshrrev_b32_e32 v143, 1, v143
	v_and_or_b32 v143, v143, 24, s17
	v_or_b32_e32 v148, s48, v143
	v_ashrrev_i32_e32 v143, 31, v142
	v_lshl_add_u64 v[144:145], v[142:143], 3, s[10:11]
	global_load_dwordx2 v[146:147], v[144:145], off
	global_load_dwordx2 v[158:159], v[144:145], off offset:128
	global_load_dwordx2 v[160:161], v[144:145], off offset:256
	global_load_dwordx2 v[162:163], v[144:145], off offset:384
	global_load_dwordx2 v[164:165], v[144:145], off offset:1024
	global_load_dwordx2 v[166:167], v[144:145], off offset:1152
	global_load_dwordx2 v[168:169], v[144:145], off offset:1280
	global_load_dwordx2 v[170:171], v[144:145], off offset:1408
	v_ashrrev_i32_e32 v149, 31, v148
	s_waitcnt vmcnt(0)
	v_ffbh_u32_e32 v143, v147
	v_min_u32_e32 v143, 32, v143
	v_lshlrev_b64 v[146:147], v143, v[146:147]
	v_min_u32_e32 v146, 1, v146
	v_or_b32_e32 v146, v147, v146
	v_cvt_f32_u32_e32 v146, v146
	v_sub_u32_e32 v143, 32, v143
	v_ldexp_f32 v143, v146, v143
	v_fmamk_f32 v143, v143, 0x31800000, v219
	v_cmp_gt_f32_e32 vcc, s86, v143
	v_mul_f32_e32 v146, 0x4b800000, v143
	s_nop 0
	v_cndmask_b32_e32 v143, v143, v146, vcc
	v_rsq_f32_e32 v143, v143
	s_nop 0
	v_mul_f32_e32 v146, 0x45800000, v143
	v_cndmask_b32_e32 v154, v143, v146, vcc
	v_pk_mul_f32 v[126:127], v[126:127], v[154:155] op_sel_hi:[1,0]
	v_pk_mul_f32 v[118:119], v[118:119], v[154:155] op_sel_hi:[1,0]
	v_mul_f32_e32 v143, 0xbfb8aa3b, v126
	v_exp_f32_e32 v143, v143
	v_pk_mul_f32 v[120:121], v[120:121], v[154:155] op_sel_hi:[1,0]
	v_pk_mul_f32 v[122:123], v[122:123], v[154:155] op_sel_hi:[1,0]
	v_pk_mul_f32 v[114:115], v[114:115], v[154:155] op_sel_hi:[1,0]
	v_add_f32_e32 v143, 1.0, v143
	v_rcp_f32_e32 v156, v143
	v_mul_f32_e32 v143, 0xbfb8aa3b, v127
	v_exp_f32_e32 v143, v143
	v_mov_b64_e32 v[146:147], s[8:9]
	v_pk_mul_f32 v[116:117], v[116:117], v[154:155] op_sel_hi:[1,0]
	v_mad_i64_i32 v[150:151], s[24:25], v142, s83, v[146:147]
	v_add_f32_e32 v143, 1.0, v143
	v_rcp_f32_e32 v157, v143
	s_nop 0
	v_pk_mul_f32 v[126:127], v[126:127], v[156:157]
	s_nop 0
	v_pk_mul_f32 v[118:119], v[118:119], v[126:127]
	v_pk_mul_f32 v[126:127], v[128:129], v[154:155] op_sel_hi:[1,0]
	v_cvt_pk_bf16_f32 v118, v118, v119
	v_mul_f32_e32 v128, 0xbfb8aa3b, v126
	v_mul_f32_e32 v129, 0xbfb8aa3b, v127
	v_exp_f32_e32 v128, v128
	v_exp_f32_e32 v129, v129
	v_add_f32_e32 v128, 1.0, v128
	v_add_f32_e32 v129, 1.0, v129
	v_rcp_f32_e32 v128, v128
	v_rcp_f32_e32 v129, v129
	s_nop 0
	v_pk_mul_f32 v[126:127], v[126:127], v[128:129]
	s_nop 0
	v_pk_mul_f32 v[120:121], v[120:121], v[126:127]
	v_mul_f32_e32 v126, 0xbfb8aa3b, v122
	v_mul_f32_e32 v127, 0xbfb8aa3b, v123
	v_exp_f32_e32 v126, v126
	v_exp_f32_e32 v127, v127
	v_cvt_pk_bf16_f32 v119, v120, v121
	v_add_f32_e32 v126, 1.0, v126
	v_add_f32_e32 v127, 1.0, v127
	v_rcp_f32_e32 v126, v126
	v_rcp_f32_e32 v127, v127
	s_nop 0
	v_pk_mul_f32 v[122:123], v[122:123], v[126:127]
	s_nop 0
	v_pk_mul_f32 v[122:123], v[114:115], v[122:123]
	v_pk_mul_f32 v[114:115], v[124:125], v[154:155] op_sel_hi:[1,0]
	v_cvt_pk_bf16_f32 v120, v122, v123
	v_mul_f32_e32 v124, 0xbfb8aa3b, v114
	v_mul_f32_e32 v125, 0xbfb8aa3b, v115
	v_exp_f32_e32 v124, v124
	v_exp_f32_e32 v125, v125
	v_add_f32_e32 v124, 1.0, v124
	v_add_f32_e32 v125, 1.0, v125
	v_rcp_f32_e32 v124, v124
	v_rcp_f32_e32 v125, v125
	s_nop 0
	v_pk_mul_f32 v[114:115], v[114:115], v[124:125]
	s_nop 0
	v_pk_mul_f32 v[116:117], v[116:117], v[114:115]
	v_lshlrev_b64 v[114:115], 1, v[148:149]
	v_lshl_add_u64 v[124:125], v[150:151], 0, v[114:115]
	v_cvt_pk_bf16_f32 v121, v116, v117
	global_store_dwordx4 v[124:125], v[118:121], off
	v_mov_b64_e32 v[116:117], v[158:159]
	s_nop 0
	v_or_b32_e32 v119, 16, v142
	s_nop 0
	v_ffbh_u32_e32 v118, v117
	v_min_u32_e32 v118, 32, v118
	v_lshlrev_b64 v[116:117], v118, v[116:117]
	v_min_u32_e32 v116, 1, v116
	v_or_b32_e32 v116, v117, v116
	v_cvt_f32_u32_e32 v116, v116
	v_sub_u32_e32 v117, 32, v118
	v_ldexp_f32 v116, v116, v117
	v_fmamk_f32 v116, v116, 0x31800000, v219
	v_cmp_gt_f32_e32 vcc, s86, v116
	v_mul_f32_e32 v117, 0x4b800000, v116
	s_nop 0
	v_cndmask_b32_e32 v116, v116, v117, vcc
	v_rsq_f32_e32 v116, v116
	s_nop 0
	v_mul_f32_e32 v117, 0x45800000, v116
	v_cndmask_b32_e32 v118, v116, v117, vcc
	v_pk_mul_f32 v[110:111], v[110:111], v[118:119] op_sel_hi:[1,0]
	v_mad_i64_i32 v[116:117], s[24:25], v119, s83, v[146:147]
	v_mul_f32_e32 v119, 0xbfb8aa3b, v110
	v_exp_f32_e32 v119, v119
	s_nop 0
	v_add_f32_e32 v119, 1.0, v119
	v_rcp_f32_e32 v120, v119
	v_pk_mul_f32 v[102:103], v[102:103], v[118:119] op_sel_hi:[1,0]
	v_mul_f32_e32 v119, 0xbfb8aa3b, v111
	v_exp_f32_e32 v119, v119
	s_nop 0
	v_add_f32_e32 v119, 1.0, v119
	v_rcp_f32_e32 v121, v119
	v_pk_mul_f32 v[104:105], v[104:105], v[118:119] op_sel_hi:[1,0]
	v_pk_mul_f32 v[106:107], v[106:107], v[118:119] op_sel_hi:[1,0]
	v_pk_mul_f32 v[98:99], v[98:99], v[118:119] op_sel_hi:[1,0]
	v_pk_mul_f32 v[110:111], v[110:111], v[120:121]
	v_pk_mul_f32 v[100:101], v[100:101], v[118:119] op_sel_hi:[1,0]
	v_pk_mul_f32 v[102:103], v[102:103], v[110:111]
	v_pk_mul_f32 v[110:111], v[112:113], v[118:119] op_sel_hi:[1,0]
	v_cvt_pk_bf16_f32 v102, v102, v103
	v_mul_f32_e32 v112, 0xbfb8aa3b, v110
	v_mul_f32_e32 v113, 0xbfb8aa3b, v111
	v_exp_f32_e32 v112, v112
	v_exp_f32_e32 v113, v113
	v_add_f32_e32 v112, 1.0, v112
	v_add_f32_e32 v113, 1.0, v113
	v_rcp_f32_e32 v112, v112
	v_rcp_f32_e32 v113, v113
	s_nop 0
	v_pk_mul_f32 v[110:111], v[110:111], v[112:113]
	s_nop 0
	v_pk_mul_f32 v[104:105], v[104:105], v[110:111]
	v_mul_f32_e32 v110, 0xbfb8aa3b, v106
	v_mul_f32_e32 v111, 0xbfb8aa3b, v107
	v_exp_f32_e32 v110, v110
	v_exp_f32_e32 v111, v111
	v_cvt_pk_bf16_f32 v103, v104, v105
	v_add_f32_e32 v110, 1.0, v110
	v_add_f32_e32 v111, 1.0, v111
	v_rcp_f32_e32 v110, v110
	v_rcp_f32_e32 v111, v111
	s_nop 0
	v_pk_mul_f32 v[106:107], v[106:107], v[110:111]
	s_nop 0
	v_pk_mul_f32 v[98:99], v[98:99], v[106:107]
	v_pk_mul_f32 v[106:107], v[108:109], v[118:119] op_sel_hi:[1,0]
	v_cvt_pk_bf16_f32 v104, v98, v99
	v_mul_f32_e32 v108, 0xbfb8aa3b, v106
	v_mul_f32_e32 v109, 0xbfb8aa3b, v107
	v_exp_f32_e32 v108, v108
	v_exp_f32_e32 v109, v109
	v_add_f32_e32 v108, 1.0, v108
	v_add_f32_e32 v109, 1.0, v109
	v_rcp_f32_e32 v108, v108
	v_rcp_f32_e32 v109, v109
	s_nop 0
	v_pk_mul_f32 v[106:107], v[106:107], v[108:109]
	s_nop 0
	v_pk_mul_f32 v[100:101], v[100:101], v[106:107]
	v_lshl_add_u64 v[106:107], v[116:117], 0, v[114:115]
	v_cvt_pk_bf16_f32 v105, v100, v101
	global_store_dwordx4 v[106:107], v[102:105], off
	v_mov_b64_e32 v[98:99], v[160:161]
	v_or_b32_e32 v101, 32, v142
	s_nop 0
	v_ffbh_u32_e32 v100, v99
	v_min_u32_e32 v100, 32, v100
	v_lshlrev_b64 v[98:99], v100, v[98:99]
	v_min_u32_e32 v98, 1, v98
	v_or_b32_e32 v98, v99, v98
	v_cvt_f32_u32_e32 v98, v98
	v_sub_u32_e32 v99, 32, v100
	v_ldexp_f32 v98, v98, v99
	v_fmamk_f32 v98, v98, 0x31800000, v219
	v_cmp_gt_f32_e32 vcc, s86, v98
	v_mul_f32_e32 v99, 0x4b800000, v98
	s_nop 0
	v_cndmask_b32_e32 v98, v98, v99, vcc
	v_rsq_f32_e32 v98, v98
	s_nop 0
	v_mul_f32_e32 v99, 0x45800000, v98
	v_cndmask_b32_e32 v100, v98, v99, vcc
	v_pk_mul_f32 v[94:95], v[94:95], v[100:101] op_sel_hi:[1,0]
	v_mad_i64_i32 v[98:99], s[24:25], v101, s83, v[146:147]
	v_mul_f32_e32 v101, 0xbfb8aa3b, v94
	v_exp_f32_e32 v101, v101
	s_nop 0
	v_add_f32_e32 v101, 1.0, v101
	v_rcp_f32_e32 v102, v101
	v_pk_mul_f32 v[86:87], v[86:87], v[100:101] op_sel_hi:[1,0]
	v_mul_f32_e32 v101, 0xbfb8aa3b, v95
	v_exp_f32_e32 v101, v101
	s_nop 0
	v_add_f32_e32 v101, 1.0, v101
	v_rcp_f32_e32 v103, v101
	v_pk_mul_f32 v[88:89], v[88:89], v[100:101] op_sel_hi:[1,0]
	v_pk_mul_f32 v[90:91], v[90:91], v[100:101] op_sel_hi:[1,0]
	v_pk_mul_f32 v[82:83], v[82:83], v[100:101] op_sel_hi:[1,0]
	v_pk_mul_f32 v[94:95], v[94:95], v[102:103]
	v_pk_mul_f32 v[84:85], v[84:85], v[100:101] op_sel_hi:[1,0]
	v_pk_mul_f32 v[86:87], v[86:87], v[94:95]
	v_pk_mul_f32 v[94:95], v[96:97], v[100:101] op_sel_hi:[1,0]
	v_cvt_pk_bf16_f32 v86, v86, v87
	v_mul_f32_e32 v96, 0xbfb8aa3b, v94
	v_mul_f32_e32 v97, 0xbfb8aa3b, v95
	v_exp_f32_e32 v96, v96
	v_exp_f32_e32 v97, v97
	v_add_f32_e32 v96, 1.0, v96
	v_add_f32_e32 v97, 1.0, v97
	v_rcp_f32_e32 v96, v96
	v_rcp_f32_e32 v97, v97
	s_nop 0
	v_pk_mul_f32 v[94:95], v[94:95], v[96:97]
	s_nop 0
	v_pk_mul_f32 v[88:89], v[88:89], v[94:95]
	v_mul_f32_e32 v94, 0xbfb8aa3b, v90
	v_mul_f32_e32 v95, 0xbfb8aa3b, v91
	v_exp_f32_e32 v94, v94
	v_exp_f32_e32 v95, v95
	v_cvt_pk_bf16_f32 v87, v88, v89
	v_add_f32_e32 v94, 1.0, v94
	v_add_f32_e32 v95, 1.0, v95
	v_rcp_f32_e32 v94, v94
	v_rcp_f32_e32 v95, v95
	s_nop 0
	v_pk_mul_f32 v[90:91], v[90:91], v[94:95]
	s_nop 0
	v_pk_mul_f32 v[82:83], v[82:83], v[90:91]
	v_pk_mul_f32 v[90:91], v[92:93], v[100:101] op_sel_hi:[1,0]
	v_cvt_pk_bf16_f32 v88, v82, v83
	v_mul_f32_e32 v92, 0xbfb8aa3b, v90
	v_mul_f32_e32 v93, 0xbfb8aa3b, v91
	v_exp_f32_e32 v92, v92
	v_exp_f32_e32 v93, v93
	v_add_f32_e32 v92, 1.0, v92
	v_add_f32_e32 v93, 1.0, v93
	v_rcp_f32_e32 v92, v92
	v_rcp_f32_e32 v93, v93
	s_nop 0
	v_pk_mul_f32 v[90:91], v[90:91], v[92:93]
	s_nop 0
	v_pk_mul_f32 v[84:85], v[84:85], v[90:91]
	v_lshl_add_u64 v[90:91], v[98:99], 0, v[114:115]
	v_cvt_pk_bf16_f32 v89, v84, v85
	global_store_dwordx4 v[90:91], v[86:89], off
	v_mov_b64_e32 v[82:83], v[162:163]
	v_or_b32_e32 v85, 48, v142
	s_nop 0
	v_ffbh_u32_e32 v84, v83
	v_min_u32_e32 v84, 32, v84
	v_lshlrev_b64 v[82:83], v84, v[82:83]
	v_min_u32_e32 v82, 1, v82
	v_or_b32_e32 v82, v83, v82
	v_cvt_f32_u32_e32 v82, v82
	v_sub_u32_e32 v83, 32, v84
	v_ldexp_f32 v82, v82, v83
	v_fmamk_f32 v82, v82, 0x31800000, v219
	v_cmp_gt_f32_e32 vcc, s86, v82
	v_mul_f32_e32 v83, 0x4b800000, v82
	s_nop 0
	v_cndmask_b32_e32 v82, v82, v83, vcc
	v_rsq_f32_e32 v82, v82
	s_nop 0
	v_mul_f32_e32 v83, 0x45800000, v82
	v_cndmask_b32_e32 v84, v82, v83, vcc
	v_pk_mul_f32 v[78:79], v[78:79], v[84:85] op_sel_hi:[1,0]
	v_mad_i64_i32 v[82:83], s[24:25], v85, s83, v[146:147]
	v_mul_f32_e32 v85, 0xbfb8aa3b, v78
	v_exp_f32_e32 v85, v85
	s_nop 0
	v_add_f32_e32 v85, 1.0, v85
	v_rcp_f32_e32 v86, v85
	v_pk_mul_f32 v[70:71], v[70:71], v[84:85] op_sel_hi:[1,0]
	v_mul_f32_e32 v85, 0xbfb8aa3b, v79
	v_exp_f32_e32 v85, v85
	s_nop 0
	v_add_f32_e32 v85, 1.0, v85
	v_rcp_f32_e32 v87, v85
	v_pk_mul_f32 v[72:73], v[72:73], v[84:85] op_sel_hi:[1,0]
	v_pk_mul_f32 v[74:75], v[74:75], v[84:85] op_sel_hi:[1,0]
	v_pk_mul_f32 v[66:67], v[66:67], v[84:85] op_sel_hi:[1,0]
	v_pk_mul_f32 v[78:79], v[78:79], v[86:87]
	v_pk_mul_f32 v[68:69], v[68:69], v[84:85] op_sel_hi:[1,0]
	v_pk_mul_f32 v[70:71], v[70:71], v[78:79]
	v_pk_mul_f32 v[78:79], v[80:81], v[84:85] op_sel_hi:[1,0]
	v_cvt_pk_bf16_f32 v70, v70, v71
	v_mul_f32_e32 v80, 0xbfb8aa3b, v78
	v_mul_f32_e32 v81, 0xbfb8aa3b, v79
	v_exp_f32_e32 v80, v80
	v_exp_f32_e32 v81, v81
	v_add_f32_e32 v80, 1.0, v80
	v_add_f32_e32 v81, 1.0, v81
	v_rcp_f32_e32 v80, v80
	v_rcp_f32_e32 v81, v81
	s_nop 0
	v_pk_mul_f32 v[78:79], v[78:79], v[80:81]
	s_nop 0
	v_pk_mul_f32 v[72:73], v[72:73], v[78:79]
	v_mul_f32_e32 v78, 0xbfb8aa3b, v74
	v_mul_f32_e32 v79, 0xbfb8aa3b, v75
	v_exp_f32_e32 v78, v78
	v_exp_f32_e32 v79, v79
	v_cvt_pk_bf16_f32 v71, v72, v73
	v_add_f32_e32 v78, 1.0, v78
	v_add_f32_e32 v79, 1.0, v79
	v_rcp_f32_e32 v78, v78
	v_rcp_f32_e32 v79, v79
	s_nop 0
	v_pk_mul_f32 v[74:75], v[74:75], v[78:79]
	s_nop 0
	v_pk_mul_f32 v[66:67], v[66:67], v[74:75]
	v_pk_mul_f32 v[74:75], v[76:77], v[84:85] op_sel_hi:[1,0]
	v_cvt_pk_bf16_f32 v72, v66, v67
	v_mul_f32_e32 v76, 0xbfb8aa3b, v74
	v_mul_f32_e32 v77, 0xbfb8aa3b, v75
	v_exp_f32_e32 v76, v76
	v_exp_f32_e32 v77, v77
	v_add_f32_e32 v76, 1.0, v76
	v_add_f32_e32 v77, 1.0, v77
	v_rcp_f32_e32 v76, v76
	v_rcp_f32_e32 v77, v77
	s_nop 0
	v_pk_mul_f32 v[74:75], v[74:75], v[76:77]
	s_nop 0
	v_pk_mul_f32 v[68:69], v[68:69], v[74:75]
	v_lshl_add_u64 v[74:75], v[82:83], 0, v[114:115]
	v_cvt_pk_bf16_f32 v73, v68, v69
	global_store_dwordx4 v[74:75], v[70:73], off
	v_mov_b64_e32 v[66:67], v[164:165]
	v_add_u32_e32 v69, 0x80, v142
	s_nop 0
	v_ffbh_u32_e32 v68, v67
	v_min_u32_e32 v68, 32, v68
	v_lshlrev_b64 v[66:67], v68, v[66:67]
	v_min_u32_e32 v66, 1, v66
	v_or_b32_e32 v66, v67, v66
	v_cvt_f32_u32_e32 v66, v66
	v_sub_u32_e32 v67, 32, v68
	v_ldexp_f32 v66, v66, v67
	v_fmamk_f32 v66, v66, 0x31800000, v219
	v_cmp_gt_f32_e32 vcc, s86, v66
	v_mul_f32_e32 v67, 0x4b800000, v66
	s_nop 0
	v_cndmask_b32_e32 v66, v66, v67, vcc
	v_rsq_f32_e32 v66, v66
	s_nop 0
	v_mul_f32_e32 v67, 0x45800000, v66
	v_cndmask_b32_e32 v68, v66, v67, vcc
	v_pk_mul_f32 v[62:63], v[62:63], v[68:69] op_sel_hi:[1,0]
	v_mad_i64_i32 v[66:67], s[24:25], v69, s83, v[146:147]
	v_mul_f32_e32 v69, 0xbfb8aa3b, v62
	v_exp_f32_e32 v69, v69
	s_nop 0
	v_add_f32_e32 v69, 1.0, v69
	v_rcp_f32_e32 v70, v69
	v_pk_mul_f32 v[54:55], v[54:55], v[68:69] op_sel_hi:[1,0]
	v_mul_f32_e32 v69, 0xbfb8aa3b, v63
	v_exp_f32_e32 v69, v69
	s_nop 0
	v_add_f32_e32 v69, 1.0, v69
	v_rcp_f32_e32 v71, v69
	v_pk_mul_f32 v[56:57], v[56:57], v[68:69] op_sel_hi:[1,0]
	v_pk_mul_f32 v[58:59], v[58:59], v[68:69] op_sel_hi:[1,0]
	v_pk_mul_f32 v[50:51], v[50:51], v[68:69] op_sel_hi:[1,0]
	v_pk_mul_f32 v[62:63], v[62:63], v[70:71]
	v_pk_mul_f32 v[52:53], v[52:53], v[68:69] op_sel_hi:[1,0]
	v_pk_mul_f32 v[54:55], v[54:55], v[62:63]
	v_pk_mul_f32 v[62:63], v[64:65], v[68:69] op_sel_hi:[1,0]
	v_cvt_pk_bf16_f32 v54, v54, v55
	v_mul_f32_e32 v64, 0xbfb8aa3b, v62
	v_mul_f32_e32 v65, 0xbfb8aa3b, v63
	v_exp_f32_e32 v64, v64
	v_exp_f32_e32 v65, v65
	v_add_f32_e32 v64, 1.0, v64
	v_add_f32_e32 v65, 1.0, v65
	v_rcp_f32_e32 v64, v64
	v_rcp_f32_e32 v65, v65
	s_nop 0
	v_pk_mul_f32 v[62:63], v[62:63], v[64:65]
	s_nop 0
	v_pk_mul_f32 v[56:57], v[56:57], v[62:63]
	v_mul_f32_e32 v62, 0xbfb8aa3b, v58
	v_mul_f32_e32 v63, 0xbfb8aa3b, v59
	v_exp_f32_e32 v62, v62
	v_exp_f32_e32 v63, v63
	v_cvt_pk_bf16_f32 v55, v56, v57
	v_add_f32_e32 v62, 1.0, v62
	v_add_f32_e32 v63, 1.0, v63
	v_rcp_f32_e32 v62, v62
	v_rcp_f32_e32 v63, v63
	s_nop 0
	v_pk_mul_f32 v[58:59], v[58:59], v[62:63]
	s_nop 0
	v_pk_mul_f32 v[50:51], v[50:51], v[58:59]
	v_pk_mul_f32 v[58:59], v[60:61], v[68:69] op_sel_hi:[1,0]
	v_cvt_pk_bf16_f32 v56, v50, v51
	v_mul_f32_e32 v60, 0xbfb8aa3b, v58
	v_mul_f32_e32 v61, 0xbfb8aa3b, v59
	v_exp_f32_e32 v60, v60
	v_exp_f32_e32 v61, v61
	v_add_f32_e32 v60, 1.0, v60
	v_add_f32_e32 v61, 1.0, v61
	v_rcp_f32_e32 v60, v60
	v_rcp_f32_e32 v61, v61
	s_nop 0
	v_pk_mul_f32 v[58:59], v[58:59], v[60:61]
	s_nop 0
	v_pk_mul_f32 v[52:53], v[52:53], v[58:59]
	v_lshl_add_u64 v[58:59], v[66:67], 0, v[114:115]
	v_cvt_pk_bf16_f32 v57, v52, v53
	global_store_dwordx4 v[58:59], v[54:57], off
	v_mov_b64_e32 v[50:51], v[166:167]
	v_add_u32_e32 v53, 0x90, v142
	s_nop 0
	v_ffbh_u32_e32 v52, v51
	v_min_u32_e32 v52, 32, v52
	v_lshlrev_b64 v[50:51], v52, v[50:51]
	v_min_u32_e32 v50, 1, v50
	v_or_b32_e32 v50, v51, v50
	v_cvt_f32_u32_e32 v50, v50
	v_sub_u32_e32 v51, 32, v52
	v_ldexp_f32 v50, v50, v51
	v_fmamk_f32 v50, v50, 0x31800000, v219
	v_cmp_gt_f32_e32 vcc, s86, v50
	v_mul_f32_e32 v51, 0x4b800000, v50
	s_nop 0
	v_cndmask_b32_e32 v50, v50, v51, vcc
	v_rsq_f32_e32 v50, v50
	s_nop 0
	v_mul_f32_e32 v51, 0x45800000, v50
	v_cndmask_b32_e32 v52, v50, v51, vcc
	v_pk_mul_f32 v[46:47], v[46:47], v[52:53] op_sel_hi:[1,0]
	v_mad_i64_i32 v[50:51], s[24:25], v53, s83, v[146:147]
	v_mul_f32_e32 v53, 0xbfb8aa3b, v46
	v_exp_f32_e32 v53, v53
	s_nop 0
	v_add_f32_e32 v53, 1.0, v53
	v_rcp_f32_e32 v54, v53
	v_pk_mul_f32 v[38:39], v[38:39], v[52:53] op_sel_hi:[1,0]
	v_mul_f32_e32 v53, 0xbfb8aa3b, v47
	v_exp_f32_e32 v53, v53
	s_nop 0
	v_add_f32_e32 v53, 1.0, v53
	v_rcp_f32_e32 v55, v53
	v_pk_mul_f32 v[40:41], v[40:41], v[52:53] op_sel_hi:[1,0]
	v_pk_mul_f32 v[42:43], v[42:43], v[52:53] op_sel_hi:[1,0]
	v_pk_mul_f32 v[34:35], v[34:35], v[52:53] op_sel_hi:[1,0]
	v_pk_mul_f32 v[46:47], v[46:47], v[54:55]
	v_pk_mul_f32 v[36:37], v[36:37], v[52:53] op_sel_hi:[1,0]
	v_pk_mul_f32 v[38:39], v[38:39], v[46:47]
	v_pk_mul_f32 v[46:47], v[48:49], v[52:53] op_sel_hi:[1,0]
	v_cvt_pk_bf16_f32 v38, v38, v39
	v_mul_f32_e32 v48, 0xbfb8aa3b, v46
	v_mul_f32_e32 v49, 0xbfb8aa3b, v47
	v_exp_f32_e32 v48, v48
	v_exp_f32_e32 v49, v49
	v_add_f32_e32 v48, 1.0, v48
	v_add_f32_e32 v49, 1.0, v49
	v_rcp_f32_e32 v48, v48
	v_rcp_f32_e32 v49, v49
	s_nop 0
	v_pk_mul_f32 v[46:47], v[46:47], v[48:49]
	s_nop 0
	v_pk_mul_f32 v[40:41], v[40:41], v[46:47]
	v_mul_f32_e32 v46, 0xbfb8aa3b, v42
	v_mul_f32_e32 v47, 0xbfb8aa3b, v43
	v_exp_f32_e32 v46, v46
	v_exp_f32_e32 v47, v47
	v_cvt_pk_bf16_f32 v39, v40, v41
	v_add_f32_e32 v46, 1.0, v46
	v_add_f32_e32 v47, 1.0, v47
	v_rcp_f32_e32 v46, v46
	v_rcp_f32_e32 v47, v47
	s_nop 0
	v_pk_mul_f32 v[42:43], v[42:43], v[46:47]
	s_nop 0
	v_pk_mul_f32 v[34:35], v[34:35], v[42:43]
	v_pk_mul_f32 v[42:43], v[44:45], v[52:53] op_sel_hi:[1,0]
	v_cvt_pk_bf16_f32 v40, v34, v35
	v_mul_f32_e32 v44, 0xbfb8aa3b, v42
	v_mul_f32_e32 v45, 0xbfb8aa3b, v43
	v_exp_f32_e32 v44, v44
	v_exp_f32_e32 v45, v45
	v_add_f32_e32 v44, 1.0, v44
	v_add_f32_e32 v45, 1.0, v45
	v_rcp_f32_e32 v44, v44
	v_rcp_f32_e32 v45, v45
	s_nop 0
	v_pk_mul_f32 v[42:43], v[42:43], v[44:45]
	s_nop 0
	v_pk_mul_f32 v[36:37], v[36:37], v[42:43]
	v_lshl_add_u64 v[42:43], v[50:51], 0, v[114:115]
	v_cvt_pk_bf16_f32 v41, v36, v37
	global_store_dwordx4 v[42:43], v[38:41], off
	v_mov_b64_e32 v[34:35], v[168:169]
	v_add_u32_e32 v37, 0xa0, v142
	s_nop 0
	v_ffbh_u32_e32 v36, v35
	v_min_u32_e32 v36, 32, v36
	v_lshlrev_b64 v[34:35], v36, v[34:35]
	v_min_u32_e32 v34, 1, v34
	v_or_b32_e32 v34, v35, v34
	v_cvt_f32_u32_e32 v34, v34
	v_sub_u32_e32 v35, 32, v36
	v_ldexp_f32 v34, v34, v35
	v_fmamk_f32 v34, v34, 0x31800000, v219
	v_cmp_gt_f32_e32 vcc, s86, v34
	v_mul_f32_e32 v35, 0x4b800000, v34
	s_nop 0
	v_cndmask_b32_e32 v34, v34, v35, vcc
	v_rsq_f32_e32 v34, v34
	s_nop 0
	v_mul_f32_e32 v35, 0x45800000, v34
	v_cndmask_b32_e32 v36, v34, v35, vcc
	v_pk_mul_f32 v[30:31], v[30:31], v[36:37] op_sel_hi:[1,0]
	v_mad_i64_i32 v[34:35], s[24:25], v37, s83, v[146:147]
	v_mul_f32_e32 v37, 0xbfb8aa3b, v30
	v_exp_f32_e32 v37, v37
	s_nop 0
	v_add_f32_e32 v37, 1.0, v37
	v_rcp_f32_e32 v38, v37
	v_pk_mul_f32 v[22:23], v[22:23], v[36:37] op_sel_hi:[1,0]
	v_mul_f32_e32 v37, 0xbfb8aa3b, v31
	v_exp_f32_e32 v37, v37
	s_nop 0
	v_add_f32_e32 v37, 1.0, v37
	v_rcp_f32_e32 v39, v37
	v_pk_mul_f32 v[24:25], v[24:25], v[36:37] op_sel_hi:[1,0]
	v_pk_mul_f32 v[26:27], v[26:27], v[36:37] op_sel_hi:[1,0]
	v_pk_mul_f32 v[18:19], v[18:19], v[36:37] op_sel_hi:[1,0]
	v_pk_mul_f32 v[30:31], v[30:31], v[38:39]
	v_pk_mul_f32 v[20:21], v[20:21], v[36:37] op_sel_hi:[1,0]
	v_pk_mul_f32 v[22:23], v[22:23], v[30:31]
	v_pk_mul_f32 v[30:31], v[32:33], v[36:37] op_sel_hi:[1,0]
	v_cvt_pk_bf16_f32 v22, v22, v23
	v_mul_f32_e32 v32, 0xbfb8aa3b, v30
	v_mul_f32_e32 v33, 0xbfb8aa3b, v31
	v_exp_f32_e32 v32, v32
	v_exp_f32_e32 v33, v33
	v_add_f32_e32 v32, 1.0, v32
	v_add_f32_e32 v33, 1.0, v33
	v_rcp_f32_e32 v32, v32
	v_rcp_f32_e32 v33, v33
	s_nop 0
	v_pk_mul_f32 v[30:31], v[30:31], v[32:33]
	s_nop 0
	v_pk_mul_f32 v[24:25], v[24:25], v[30:31]
	v_mul_f32_e32 v30, 0xbfb8aa3b, v26
	v_mul_f32_e32 v31, 0xbfb8aa3b, v27
	v_exp_f32_e32 v30, v30
	v_exp_f32_e32 v31, v31
	v_cvt_pk_bf16_f32 v23, v24, v25
	v_add_f32_e32 v30, 1.0, v30
	v_add_f32_e32 v31, 1.0, v31
	v_rcp_f32_e32 v30, v30
	v_rcp_f32_e32 v31, v31
	s_nop 0
	v_pk_mul_f32 v[26:27], v[26:27], v[30:31]
	s_nop 0
	v_pk_mul_f32 v[18:19], v[18:19], v[26:27]
	v_pk_mul_f32 v[26:27], v[28:29], v[36:37] op_sel_hi:[1,0]
	v_cvt_pk_bf16_f32 v24, v18, v19
	v_mul_f32_e32 v28, 0xbfb8aa3b, v26
	v_mul_f32_e32 v29, 0xbfb8aa3b, v27
	v_exp_f32_e32 v28, v28
	v_exp_f32_e32 v29, v29
	v_add_f32_e32 v28, 1.0, v28
	v_add_f32_e32 v29, 1.0, v29
	v_rcp_f32_e32 v28, v28
	v_rcp_f32_e32 v29, v29
	s_nop 0
	v_pk_mul_f32 v[26:27], v[26:27], v[28:29]
	s_nop 0
	v_pk_mul_f32 v[20:21], v[20:21], v[26:27]
	v_lshl_add_u64 v[26:27], v[34:35], 0, v[114:115]
	v_cvt_pk_bf16_f32 v25, v20, v21
	global_store_dwordx4 v[26:27], v[22:25], off
	v_mov_b64_e32 v[18:19], v[170:171]
	v_add_u32_e32 v20, 0xb0, v142
	s_nop 0
	v_ffbh_u32_e32 v21, v19
	v_min_u32_e32 v21, 32, v21
	v_lshlrev_b64 v[18:19], v21, v[18:19]
	v_min_u32_e32 v18, 1, v18
	v_or_b32_e32 v18, v19, v18
	v_cvt_f32_u32_e32 v18, v18
	v_sub_u32_e32 v19, 32, v21
	v_mad_i64_i32 v[20:21], s[24:25], v20, s83, v[146:147]
	v_ldexp_f32 v18, v18, v19
	v_fmamk_f32 v18, v18, 0x31800000, v219
	v_cmp_gt_f32_e32 vcc, s86, v18
	v_mul_f32_e32 v19, 0x4b800000, v18
	s_mov_b64 s[24:25], -1
	v_cndmask_b32_e32 v18, v18, v19, vcc
	v_rsq_f32_e32 v18, v18
	s_nop 0
	v_mul_f32_e32 v19, 0x45800000, v18
	v_cndmask_b32_e32 v18, v18, v19, vcc
	v_pk_mul_f32 v[14:15], v[14:15], v[18:19] op_sel_hi:[1,0]
	s_andn2_b64 vcc, exec, s[2:3]
	v_mul_f32_e32 v19, 0xbfb8aa3b, v14
	v_exp_f32_e32 v19, v19
	s_nop 0
	v_add_f32_e32 v19, 1.0, v19
	v_rcp_f32_e32 v22, v19
	v_pk_mul_f32 v[6:7], v[6:7], v[18:19] op_sel_hi:[1,0]
	v_mul_f32_e32 v19, 0xbfb8aa3b, v15
	v_exp_f32_e32 v19, v19
	s_nop 0
	v_add_f32_e32 v19, 1.0, v19
	v_rcp_f32_e32 v23, v19
	v_pk_mul_f32 v[8:9], v[8:9], v[18:19] op_sel_hi:[1,0]
	v_pk_mul_f32 v[10:11], v[10:11], v[18:19] op_sel_hi:[1,0]
	v_pk_mul_f32 v[2:3], v[2:3], v[18:19] op_sel_hi:[1,0]
	v_pk_mul_f32 v[14:15], v[14:15], v[22:23]
	v_pk_mul_f32 v[4:5], v[4:5], v[18:19] op_sel_hi:[1,0]
	v_pk_mul_f32 v[6:7], v[6:7], v[14:15]
	v_pk_mul_f32 v[14:15], v[16:17], v[18:19] op_sel_hi:[1,0]
	s_nop 0
	v_mul_f32_e32 v16, 0xbfb8aa3b, v14
	v_mul_f32_e32 v17, 0xbfb8aa3b, v15
	v_exp_f32_e32 v16, v16
	v_exp_f32_e32 v17, v17
	v_add_f32_e32 v16, 1.0, v16
	v_add_f32_e32 v17, 1.0, v17
	v_rcp_f32_e32 v16, v16
	v_rcp_f32_e32 v17, v17
	s_nop 0
	v_pk_mul_f32 v[14:15], v[14:15], v[16:17]
	s_nop 0
	v_pk_mul_f32 v[8:9], v[8:9], v[14:15]
	v_mul_f32_e32 v14, 0xbfb8aa3b, v10
	v_mul_f32_e32 v15, 0xbfb8aa3b, v11
	v_exp_f32_e32 v14, v14
	v_exp_f32_e32 v15, v15
	v_add_f32_e32 v14, 1.0, v14
	v_add_f32_e32 v15, 1.0, v15
	v_rcp_f32_e32 v14, v14
	v_rcp_f32_e32 v15, v15
	s_nop 0
	v_pk_mul_f32 v[10:11], v[10:11], v[14:15]
	s_nop 0
	v_pk_mul_f32 v[10:11], v[2:3], v[10:11]
	v_pk_mul_f32 v[2:3], v[12:13], v[18:19] op_sel_hi:[1,0]
	v_lshl_add_u64 v[14:15], v[20:21], 0, v[114:115]
	v_mul_f32_e32 v12, 0xbfb8aa3b, v2
	v_mul_f32_e32 v13, 0xbfb8aa3b, v3
	v_exp_f32_e32 v12, v12
	v_exp_f32_e32 v13, v13
	v_add_f32_e32 v12, 1.0, v12
	v_add_f32_e32 v13, 1.0, v13
	v_rcp_f32_e32 v12, v12
	v_rcp_f32_e32 v13, v13
	s_nop 0
	v_pk_mul_f32 v[2:3], v[2:3], v[12:13]
	s_nop 0
	v_pk_mul_f32 v[12:13], v[4:5], v[2:3]
	v_cvt_pk_bf16_f32 v2, v6, v7
	v_cvt_pk_bf16_f32 v3, v8, v9
	v_cvt_pk_bf16_f32 v4, v10, v11
	v_cvt_pk_bf16_f32 v5, v12, v13
	global_store_dwordx4 v[14:15], v[2:5], off
	s_cbranch_vccnz .LBB0_107
	s_andn2_b64 vcc, exec, s[6:7]
	s_cbranch_vccnz .LBB0_106
	s_barrier
	s_branch .LBB0_106

.LBB0_194:
	s_or_b64 exec, exec, s[4:5]
	s_mov_b64 s[4:5], exec
	v_mbcnt_lo_u32_b32 v1, s4, 0
	v_mbcnt_hi_u32_b32 v1, s5, v1
	v_cmp_eq_u32_e32 vcc, 0, v1
	s_and_saveexec_b64 s[8:9], vcc
	s_cbranch_execz .LBB0_196
	s_bcnt1_i32_b64 s4, s[4:5]
	v_mov_b32_e32 v1, s4
	global_atomic_add v254, v1, s[6:7] offset:1024

.LBB0_312:
	s_or_b64 exec, exec, s[6:7]
	s_mov_b64 s[6:7], exec
	v_mbcnt_lo_u32_b32 v1, s6, 0
	v_mbcnt_hi_u32_b32 v1, s7, v1
	v_cmp_eq_u32_e32 vcc, 0, v1
	s_and_saveexec_b64 s[8:9], vcc
	s_cbranch_execz .LBB0_314
	s_bcnt1_i32_b64 s6, s[6:7]
	v_mov_b32_e32 v1, s6
	global_atomic_add v254, v1, s[4:5] offset:1024

.LBB0_329:
	v_mov_b32_e32 v167, v218
	s_lshl_b32 s5, s4, 8
	v_and_b32_e32 v164, 15, v167
	v_or_b32_e32 v142, s58, v164
	v_add_u32_e32 v142, s5, v142
	v_ashrrev_i32_e32 v143, 31, v142
	v_lshl_add_u64 v[158:159], v[142:143], 3, s[12:13]
	global_load_dwordx2 v[144:145], v[158:159], off
	global_load_dwordx2 v[176:177], v[158:159], off offset:128
	global_load_dwordx2 v[178:179], v[158:159], off offset:256
	global_load_dwordx2 v[180:181], v[158:159], off offset:384
	global_load_dwordx2 v[182:183], v[158:159], off offset:1024
	global_load_dwordx2 v[184:185], v[158:159], off offset:1152
	global_load_dwordx2 v[186:187], v[158:159], off offset:1280
	global_load_dwordx2 v[188:189], v[158:159], off offset:1408
	v_bfe_u32 v165, v167, 4, 2
	v_lshlrev_b32_e32 v168, 3, v165
	v_or_b32_e32 v169, s59, v168
	s_mov_b64 s[28:29], -1
	s_cmp_gt_i32 s26, 1
	s_waitcnt vmcnt(0)
	v_ffbh_u32_e32 v146, v145
	v_min_u32_e32 v146, 32, v146
	v_lshlrev_b64 v[144:145], v146, v[144:145]
	v_min_u32_e32 v144, 1, v144
	v_or_b32_e32 v144, v145, v144
	v_cvt_f32_u32_e32 v144, v144
	v_sub_u32_e32 v145, 32, v146
	v_ldexp_f32 v144, v144, v145
	v_fmamk_f32 v144, v144, 0x31800000, v219
	v_cmp_gt_f32_e32 vcc, s86, v144
	v_mul_f32_e32 v145, 0x4b800000, v144
	s_nop 0
	v_cndmask_b32_e32 v144, v144, v145, vcc
	v_rsq_f32_e32 v144, v144
	s_nop 0
	v_mul_f32_e32 v145, 0x45800000, v144
	v_cndmask_b32_e32 v146, v144, v145, vcc
	v_pk_mul_f32 v[128:129], v[128:129], v[146:147] op_sel_hi:[1,0]
	v_pk_mul_f32 v[126:127], v[126:127], v[146:147] op_sel_hi:[1,0]
	v_pk_mul_f32 v[124:125], v[124:125], v[146:147] op_sel_hi:[1,0]
	v_pk_mul_f32 v[122:123], v[122:123], v[146:147] op_sel_hi:[1,0]
	v_pk_mul_f32 v[120:121], v[120:121], v[146:147] op_sel_hi:[1,0]
	v_pk_mul_f32 v[144:145], v[118:119], v[146:147] op_sel_hi:[1,0]
	v_pk_mul_f32 v[116:117], v[116:117], v[146:147] op_sel_hi:[1,0]
	v_pk_mul_f32 v[118:119], v[114:115], v[146:147] op_sel_hi:[1,0]
	v_mov_b64_e32 v[146:147], v[176:177]
	v_or_b32_e32 v114, 16, v142
	v_ashrrev_i32_e32 v115, 31, v114
	s_nop 0
	v_ffbh_u32_e32 v148, v147
	v_min_u32_e32 v148, 32, v148
	v_lshlrev_b64 v[146:147], v148, v[146:147]
	v_min_u32_e32 v146, 1, v146
	v_or_b32_e32 v146, v147, v146
	v_cvt_f32_u32_e32 v146, v146
	v_sub_u32_e32 v147, 32, v148
	v_ldexp_f32 v146, v146, v147
	v_fmamk_f32 v146, v146, 0x31800000, v219
	v_cmp_gt_f32_e32 vcc, s86, v146
	v_mul_f32_e32 v147, 0x4b800000, v146
	s_nop 0
	v_cndmask_b32_e32 v146, v146, v147, vcc
	v_rsq_f32_e32 v146, v146
	s_nop 0
	v_mul_f32_e32 v147, 0x45800000, v146
	v_cndmask_b32_e32 v148, v146, v147, vcc
	v_pk_mul_f32 v[112:113], v[112:113], v[148:149] op_sel_hi:[1,0]
	v_pk_mul_f32 v[110:111], v[110:111], v[148:149] op_sel_hi:[1,0]
	v_pk_mul_f32 v[108:109], v[108:109], v[148:149] op_sel_hi:[1,0]
	v_pk_mul_f32 v[106:107], v[106:107], v[148:149] op_sel_hi:[1,0]
	v_pk_mul_f32 v[104:105], v[104:105], v[148:149] op_sel_hi:[1,0]
	v_pk_mul_f32 v[146:147], v[102:103], v[148:149] op_sel_hi:[1,0]
	v_pk_mul_f32 v[100:101], v[100:101], v[148:149] op_sel_hi:[1,0]
	v_pk_mul_f32 v[102:103], v[98:99], v[148:149] op_sel_hi:[1,0]
	v_mov_b64_e32 v[148:149], v[178:179]
	v_or_b32_e32 v98, 32, v142
	v_ashrrev_i32_e32 v99, 31, v98
	s_nop 0
	v_ffbh_u32_e32 v150, v149
	v_min_u32_e32 v150, 32, v150
	v_lshlrev_b64 v[148:149], v150, v[148:149]
	v_min_u32_e32 v148, 1, v148
	v_or_b32_e32 v148, v149, v148
	v_cvt_f32_u32_e32 v148, v148
	v_sub_u32_e32 v149, 32, v150
	v_ldexp_f32 v148, v148, v149
	v_fmamk_f32 v148, v148, 0x31800000, v219
	v_cmp_gt_f32_e32 vcc, s86, v148
	v_mul_f32_e32 v149, 0x4b800000, v148
	s_nop 0
	v_cndmask_b32_e32 v148, v148, v149, vcc
	v_rsq_f32_e32 v148, v148
	s_nop 0
	v_mul_f32_e32 v149, 0x45800000, v148
	v_cndmask_b32_e32 v150, v148, v149, vcc
	v_pk_mul_f32 v[96:97], v[96:97], v[150:151] op_sel_hi:[1,0]
	v_pk_mul_f32 v[94:95], v[94:95], v[150:151] op_sel_hi:[1,0]
	v_pk_mul_f32 v[92:93], v[92:93], v[150:151] op_sel_hi:[1,0]
	v_pk_mul_f32 v[90:91], v[90:91], v[150:151] op_sel_hi:[1,0]
	v_pk_mul_f32 v[88:89], v[88:89], v[150:151] op_sel_hi:[1,0]
	v_pk_mul_f32 v[148:149], v[86:87], v[150:151] op_sel_hi:[1,0]
	v_pk_mul_f32 v[84:85], v[84:85], v[150:151] op_sel_hi:[1,0]
	v_pk_mul_f32 v[86:87], v[82:83], v[150:151] op_sel_hi:[1,0]
	v_mov_b64_e32 v[150:151], v[180:181]
	v_or_b32_e32 v82, 48, v142
	v_ashrrev_i32_e32 v83, 31, v82
	s_nop 0
	v_ffbh_u32_e32 v152, v151
	v_min_u32_e32 v152, 32, v152
	v_lshlrev_b64 v[150:151], v152, v[150:151]
	v_min_u32_e32 v150, 1, v150
	v_or_b32_e32 v150, v151, v150
	v_cvt_f32_u32_e32 v150, v150
	v_sub_u32_e32 v151, 32, v152
	v_ldexp_f32 v150, v150, v151
	v_fmamk_f32 v150, v150, 0x31800000, v219
	v_cmp_gt_f32_e32 vcc, s86, v150
	v_mul_f32_e32 v151, 0x4b800000, v150
	s_nop 0
	v_cndmask_b32_e32 v150, v150, v151, vcc
	v_rsq_f32_e32 v150, v150
	s_nop 0
	v_mul_f32_e32 v151, 0x45800000, v150
	v_cndmask_b32_e32 v152, v150, v151, vcc
	v_pk_mul_f32 v[80:81], v[80:81], v[152:153] op_sel_hi:[1,0]
	v_pk_mul_f32 v[78:79], v[78:79], v[152:153] op_sel_hi:[1,0]
	v_pk_mul_f32 v[76:77], v[76:77], v[152:153] op_sel_hi:[1,0]
	v_pk_mul_f32 v[74:75], v[74:75], v[152:153] op_sel_hi:[1,0]
	v_pk_mul_f32 v[72:73], v[72:73], v[152:153] op_sel_hi:[1,0]
	v_pk_mul_f32 v[150:151], v[70:71], v[152:153] op_sel_hi:[1,0]
	v_pk_mul_f32 v[68:69], v[68:69], v[152:153] op_sel_hi:[1,0]
	v_pk_mul_f32 v[70:71], v[66:67], v[152:153] op_sel_hi:[1,0]
	v_mov_b64_e32 v[152:153], v[182:183]
	v_add_u32_e32 v66, 0x80, v142
	v_ashrrev_i32_e32 v67, 31, v66
	s_nop 0
	v_ffbh_u32_e32 v154, v153
	v_min_u32_e32 v154, 32, v154
	v_lshlrev_b64 v[152:153], v154, v[152:153]
	v_min_u32_e32 v152, 1, v152
	v_or_b32_e32 v152, v153, v152
	v_cvt_f32_u32_e32 v152, v152
	v_sub_u32_e32 v153, 32, v154
	v_ldexp_f32 v152, v152, v153
	v_fmamk_f32 v152, v152, 0x31800000, v219
	v_cmp_gt_f32_e32 vcc, s86, v152
	v_mul_f32_e32 v153, 0x4b800000, v152
	s_nop 0
	v_cndmask_b32_e32 v152, v152, v153, vcc
	v_rsq_f32_e32 v152, v152
	s_nop 0
	v_mul_f32_e32 v153, 0x45800000, v152
	v_cndmask_b32_e32 v154, v152, v153, vcc
	v_pk_mul_f32 v[64:65], v[64:65], v[154:155] op_sel_hi:[1,0]
	v_pk_mul_f32 v[62:63], v[62:63], v[154:155] op_sel_hi:[1,0]
	v_pk_mul_f32 v[60:61], v[60:61], v[154:155] op_sel_hi:[1,0]
	v_pk_mul_f32 v[58:59], v[58:59], v[154:155] op_sel_hi:[1,0]
	v_pk_mul_f32 v[56:57], v[56:57], v[154:155] op_sel_hi:[1,0]
	v_pk_mul_f32 v[152:153], v[54:55], v[154:155] op_sel_hi:[1,0]
	v_pk_mul_f32 v[52:53], v[52:53], v[154:155] op_sel_hi:[1,0]
	v_pk_mul_f32 v[54:55], v[50:51], v[154:155] op_sel_hi:[1,0]
	v_mov_b64_e32 v[154:155], v[184:185]
	v_add_u32_e32 v50, 0x90, v142
	v_ashrrev_i32_e32 v51, 31, v50
	s_nop 0
	v_ffbh_u32_e32 v156, v155
	v_min_u32_e32 v156, 32, v156
	v_lshlrev_b64 v[154:155], v156, v[154:155]
	v_min_u32_e32 v154, 1, v154
	v_or_b32_e32 v154, v155, v154
	v_cvt_f32_u32_e32 v154, v154
	v_sub_u32_e32 v155, 32, v156
	v_ldexp_f32 v154, v154, v155
	v_fmamk_f32 v154, v154, 0x31800000, v219
	v_cmp_gt_f32_e32 vcc, s86, v154
	v_mul_f32_e32 v155, 0x4b800000, v154
	s_nop 0
	v_cndmask_b32_e32 v154, v154, v155, vcc
	v_rsq_f32_e32 v154, v154
	s_nop 0
	v_mul_f32_e32 v155, 0x45800000, v154
	v_cndmask_b32_e32 v156, v154, v155, vcc
	v_pk_mul_f32 v[48:49], v[48:49], v[156:157] op_sel_hi:[1,0]
	v_pk_mul_f32 v[46:47], v[46:47], v[156:157] op_sel_hi:[1,0]
	v_pk_mul_f32 v[44:45], v[44:45], v[156:157] op_sel_hi:[1,0]
	v_pk_mul_f32 v[42:43], v[42:43], v[156:157] op_sel_hi:[1,0]
	v_pk_mul_f32 v[40:41], v[40:41], v[156:157] op_sel_hi:[1,0]
	v_pk_mul_f32 v[154:155], v[38:39], v[156:157] op_sel_hi:[1,0]
	v_pk_mul_f32 v[36:37], v[36:37], v[156:157] op_sel_hi:[1,0]
	v_pk_mul_f32 v[38:39], v[34:35], v[156:157] op_sel_hi:[1,0]
	v_mov_b64_e32 v[156:157], v[186:187]
	v_add_u32_e32 v34, 0xa0, v142
	v_mov_b64_e32 v[158:159], v[188:189]
	v_ashrrev_i32_e32 v35, 31, v34
	s_nop 0
	v_ffbh_u32_e32 v160, v157
	v_min_u32_e32 v160, 32, v160
	v_lshlrev_b64 v[156:157], v160, v[156:157]
	v_min_u32_e32 v156, 1, v156
	v_or_b32_e32 v156, v157, v156
	v_cvt_f32_u32_e32 v156, v156
	v_sub_u32_e32 v157, 32, v160
	v_ldexp_f32 v156, v156, v157
	v_fmamk_f32 v156, v156, 0x31800000, v219
	v_cmp_gt_f32_e32 vcc, s86, v156
	v_mul_f32_e32 v157, 0x4b800000, v156
	s_nop 0
	v_cndmask_b32_e32 v156, v156, v157, vcc
	v_rsq_f32_e32 v156, v156
	s_nop 0
	v_mul_f32_e32 v157, 0x45800000, v156
	v_cndmask_b32_e32 v160, v156, v157, vcc
	v_pk_mul_f32 v[32:33], v[32:33], v[160:161] op_sel_hi:[1,0]
	v_pk_mul_f32 v[30:31], v[30:31], v[160:161] op_sel_hi:[1,0]
	v_pk_mul_f32 v[28:29], v[28:29], v[160:161] op_sel_hi:[1,0]
	v_pk_mul_f32 v[26:27], v[26:27], v[160:161] op_sel_hi:[1,0]
	v_pk_mul_f32 v[24:25], v[24:25], v[160:161] op_sel_hi:[1,0]
	v_pk_mul_f32 v[156:157], v[22:23], v[160:161] op_sel_hi:[1,0]
	v_pk_mul_f32 v[20:21], v[20:21], v[160:161] op_sel_hi:[1,0]
	v_pk_mul_f32 v[22:23], v[18:19], v[160:161] op_sel_hi:[1,0]
	s_nop 0
	v_ffbh_u32_e32 v160, v159
	v_min_u32_e32 v160, 32, v160
	v_lshlrev_b64 v[158:159], v160, v[158:159]
	v_min_u32_e32 v158, 1, v158
	v_or_b32_e32 v158, v159, v158
	v_cvt_f32_u32_e32 v158, v158
	v_sub_u32_e32 v159, 32, v160
	v_add_u32_e32 v18, 0xb0, v142
	v_ashrrev_i32_e32 v19, 31, v18
	v_ldexp_f32 v158, v158, v159
	v_fmamk_f32 v158, v158, 0x31800000, v219
	v_cmp_gt_f32_e32 vcc, s86, v158
	v_mul_f32_e32 v159, 0x4b800000, v158
	s_nop 0
	v_cndmask_b32_e32 v158, v158, v159, vcc
	v_rsq_f32_e32 v158, v158
	s_nop 0
	v_mul_f32_e32 v159, 0x45800000, v158
	v_cndmask_b32_e32 v158, v158, v159, vcc
	v_pk_mul_f32 v[16:17], v[16:17], v[158:159] op_sel_hi:[1,0]
	v_pk_mul_f32 v[14:15], v[14:15], v[158:159] op_sel_hi:[1,0]
	v_pk_mul_f32 v[12:13], v[12:13], v[158:159] op_sel_hi:[1,0]
	v_pk_mul_f32 v[10:11], v[10:11], v[158:159] op_sel_hi:[1,0]
	v_pk_mul_f32 v[8:9], v[8:9], v[158:159] op_sel_hi:[1,0]
	v_pk_mul_f32 v[6:7], v[6:7], v[158:159] op_sel_hi:[1,0]
	v_pk_mul_f32 v[4:5], v[4:5], v[158:159] op_sel_hi:[1,0]
	v_pk_mul_f32 v[2:3], v[2:3], v[158:159] op_sel_hi:[1,0]
	s_cbranch_scc0 .LBB0_339
	s_cmp_eq_u32 s26, 4
	s_cselect_b64 s[28:29], -1, 0
	s_cmp_lg_u32 s26, 4
	s_cselect_b64 s[30:31], -1, 0
	s_and_b32 s19, s26, 0x7ffffffe
	s_cmp_lg_u32 s19, 6
	s_cselect_b64 s[34:35], -1, 0
	s_and_b64 s[34:35], s[30:31], s[34:35]
	s_mov_b64 s[30:31], -1
	s_and_b64 vcc, exec, s[34:35]
	s_cbranch_vccz .LBB0_336
	s_cmp_lt_u32 s26, 8
	s_cbranch_scc0 .LBB0_333
	s_cmp_eq_u32 s26, 3
	s_movk_i32 s19, 0x300
	s_cselect_b32 s19, 0x200, s19
	s_cmp_lg_u32 s26, 2
	v_lshlrev_b64 v[158:159], 11, v[142:143]
	s_cselect_b32 s19, s19, 0x100
	v_lshl_add_u64 v[158:159], s[10:11], 0, v[158:159]
	s_lshl_b32 s80, s19, 1
	v_lshl_add_u64 v[158:159], v[158:159], 0, s[80:81]
	v_lshlrev_b32_e32 v162, 1, v169
	v_mov_b32_e32 v163, v0
	v_lshl_add_u64 v[170:171], v[158:159], 0, v[162:163]
	v_cvt_pk_bf16_f32 v158, v126, v127
	v_cvt_pk_bf16_f32 v159, v128, v129
	v_cvt_pk_bf16_f32 v160, v122, v123
	v_cvt_pk_bf16_f32 v161, v124, v125
	global_store_dwordx4 v[170:171], v[158:161], off
	s_mov_b64 s[30:31], 0
	s_nop 0
	v_cvt_pk_bf16_f32 v158, v144, v145
	v_cvt_pk_bf16_f32 v159, v120, v121
	v_cvt_pk_bf16_f32 v160, v118, v119
	v_cvt_pk_bf16_f32 v161, v116, v117
	global_store_dwordx4 v[170:171], v[158:161], off offset:256
	s_nop 1
	v_lshlrev_b64 v[158:159], 11, v[114:115]
	v_lshl_add_u64 v[158:159], s[10:11], 0, v[158:159]
	v_lshl_add_u64 v[158:159], v[158:159], 0, s[80:81]
	v_lshl_add_u64 v[170:171], v[158:159], 0, v[162:163]
	v_cvt_pk_bf16_f32 v158, v110, v111
	v_cvt_pk_bf16_f32 v159, v112, v113
	v_cvt_pk_bf16_f32 v160, v106, v107
	v_cvt_pk_bf16_f32 v161, v108, v109
	global_store_dwordx4 v[170:171], v[158:161], off
	s_nop 1
	v_cvt_pk_bf16_f32 v158, v146, v147
	v_cvt_pk_bf16_f32 v159, v104, v105
	v_cvt_pk_bf16_f32 v160, v102, v103
	v_cvt_pk_bf16_f32 v161, v100, v101
	global_store_dwordx4 v[170:171], v[158:161], off offset:256
	s_nop 1
	v_lshlrev_b64 v[158:159], 11, v[98:99]
	v_lshl_add_u64 v[158:159], s[10:11], 0, v[158:159]
	v_lshl_add_u64 v[158:159], v[158:159], 0, s[80:81]
	v_lshl_add_u64 v[170:171], v[158:159], 0, v[162:163]
	v_cvt_pk_bf16_f32 v158, v94, v95
	v_cvt_pk_bf16_f32 v159, v96, v97
	v_cvt_pk_bf16_f32 v160, v90, v91
	v_cvt_pk_bf16_f32 v161, v92, v93
	global_store_dwordx4 v[170:171], v[158:161], off
	s_nop 1
	v_cvt_pk_bf16_f32 v158, v148, v149
	v_cvt_pk_bf16_f32 v159, v88, v89
	v_cvt_pk_bf16_f32 v160, v86, v87
	v_cvt_pk_bf16_f32 v161, v84, v85
	global_store_dwordx4 v[170:171], v[158:161], off offset:256
	s_nop 1
	v_lshlrev_b64 v[158:159], 11, v[82:83]
	v_lshl_add_u64 v[158:159], s[10:11], 0, v[158:159]
	v_lshl_add_u64 v[158:159], v[158:159], 0, s[80:81]
	v_lshl_add_u64 v[170:171], v[158:159], 0, v[162:163]
	v_cvt_pk_bf16_f32 v158, v78, v79
	v_cvt_pk_bf16_f32 v159, v80, v81
	v_cvt_pk_bf16_f32 v160, v74, v75
	v_cvt_pk_bf16_f32 v161, v76, v77
	global_store_dwordx4 v[170:171], v[158:161], off
	s_nop 1
	v_cvt_pk_bf16_f32 v158, v150, v151
	v_cvt_pk_bf16_f32 v159, v72, v73
	v_cvt_pk_bf16_f32 v160, v70, v71
	v_cvt_pk_bf16_f32 v161, v68, v69
	global_store_dwordx4 v[170:171], v[158:161], off offset:256
	s_nop 1
	v_lshlrev_b64 v[158:159], 11, v[66:67]
	v_lshl_add_u64 v[158:159], s[10:11], 0, v[158:159]
	v_lshl_add_u64 v[158:159], v[158:159], 0, s[80:81]
	v_lshl_add_u64 v[170:171], v[158:159], 0, v[162:163]
	v_cvt_pk_bf16_f32 v158, v62, v63
	v_cvt_pk_bf16_f32 v159, v64, v65
	v_cvt_pk_bf16_f32 v160, v58, v59
	v_cvt_pk_bf16_f32 v161, v60, v61
	global_store_dwordx4 v[170:171], v[158:161], off
	s_nop 1
	v_cvt_pk_bf16_f32 v158, v152, v153
	v_cvt_pk_bf16_f32 v159, v56, v57
	v_cvt_pk_bf16_f32 v160, v54, v55
	v_cvt_pk_bf16_f32 v161, v52, v53
	global_store_dwordx4 v[170:171], v[158:161], off offset:256
	s_nop 1
	v_lshlrev_b64 v[158:159], 11, v[50:51]
	v_lshl_add_u64 v[158:159], s[10:11], 0, v[158:159]
	v_lshl_add_u64 v[158:159], v[158:159], 0, s[80:81]
	v_lshl_add_u64 v[170:171], v[158:159], 0, v[162:163]
	v_cvt_pk_bf16_f32 v158, v46, v47
	v_cvt_pk_bf16_f32 v159, v48, v49
	v_cvt_pk_bf16_f32 v160, v42, v43
	v_cvt_pk_bf16_f32 v161, v44, v45
	global_store_dwordx4 v[170:171], v[158:161], off
	s_nop 1
	v_cvt_pk_bf16_f32 v158, v154, v155
	v_cvt_pk_bf16_f32 v159, v40, v41
	v_cvt_pk_bf16_f32 v160, v38, v39
	v_cvt_pk_bf16_f32 v161, v36, v37
	global_store_dwordx4 v[170:171], v[158:161], off offset:256
	s_nop 1
	v_lshlrev_b64 v[158:159], 11, v[34:35]
	v_lshl_add_u64 v[158:159], s[10:11], 0, v[158:159]
	v_lshl_add_u64 v[158:159], v[158:159], 0, s[80:81]
	v_lshl_add_u64 v[170:171], v[158:159], 0, v[162:163]
	v_cvt_pk_bf16_f32 v158, v30, v31
	v_cvt_pk_bf16_f32 v159, v32, v33
	v_cvt_pk_bf16_f32 v160, v26, v27
	v_cvt_pk_bf16_f32 v161, v28, v29
	global_store_dwordx4 v[170:171], v[158:161], off
	s_nop 1
	v_cvt_pk_bf16_f32 v158, v156, v157
	v_cvt_pk_bf16_f32 v159, v24, v25
	v_cvt_pk_bf16_f32 v160, v22, v23
	v_cvt_pk_bf16_f32 v161, v20, v21
	global_store_dwordx4 v[170:171], v[158:161], off offset:256
	s_nop 1
	v_lshlrev_b64 v[158:159], 11, v[18:19]
	v_lshl_add_u64 v[158:159], s[10:11], 0, v[158:159]
	v_lshl_add_u64 v[158:159], v[158:159], 0, s[80:81]
	v_lshl_add_u64 v[162:163], v[158:159], 0, v[162:163]
	v_cvt_pk_bf16_f32 v158, v14, v15
	v_cvt_pk_bf16_f32 v159, v16, v17
	v_cvt_pk_bf16_f32 v160, v10, v11
	v_cvt_pk_bf16_f32 v161, v12, v13
	global_store_dwordx4 v[162:163], v[158:161], off
	s_nop 1
	v_cvt_pk_bf16_f32 v158, v6, v7
	v_cvt_pk_bf16_f32 v159, v8, v9
	v_cvt_pk_bf16_f32 v160, v2, v3
	v_cvt_pk_bf16_f32 v161, v4, v5
	global_store_dwordx4 v[162:163], v[158:161], off offset:256

.LBB0_867:
	s_or_b64 exec, exec, s[6:7]
	s_mov_b64 s[6:7], exec
	v_mbcnt_lo_u32_b32 v1, s6, 0
	v_mbcnt_hi_u32_b32 v1, s7, v1
	v_cmp_eq_u32_e32 vcc, 0, v1
	s_and_saveexec_b64 s[10:11], vcc
	s_cbranch_execz .LBB0_869
	s_bcnt1_i32_b64 s6, s[6:7]
	v_mov_b32_e32 v1, s6
	global_atomic_add v254, v1, s[4:5] offset:1024
.LBB0_869:
	s_or_b64 exec, exec, s[10:11]
	buffer_inv sc1
	s_waitcnt vmcnt(0)

.LBB0_1183:
	v_mov_b32_e32 v143, v218
	s_lshl_b32 s15, s22, 8
	s_add_i32 s15, s15, s45
	v_and_or_b32 v142, v143, 15, s15
	s_lshl_b32 s15, s23, 7
	v_lshrrev_b32_e32 v143, 1, v143
	v_and_or_b32 v143, v143, 24, s15
	v_or_b32_e32 v148, s46, v143
	v_ashrrev_i32_e32 v143, 31, v142
	v_lshl_add_u64 v[144:145], v[142:143], 3, s[10:11]
	global_load_dwordx2 v[146:147], v[144:145], off
	global_load_dwordx2 v[158:159], v[144:145], off offset:128
	global_load_dwordx2 v[160:161], v[144:145], off offset:256
	global_load_dwordx2 v[162:163], v[144:145], off offset:384
	global_load_dwordx2 v[164:165], v[144:145], off offset:1024
	global_load_dwordx2 v[166:167], v[144:145], off offset:1152
	global_load_dwordx2 v[168:169], v[144:145], off offset:1280
	global_load_dwordx2 v[170:171], v[144:145], off offset:1408
	v_ashrrev_i32_e32 v149, 31, v148
	s_waitcnt vmcnt(0)
	v_ffbh_u32_e32 v143, v147
	v_min_u32_e32 v143, 32, v143
	v_lshlrev_b64 v[146:147], v143, v[146:147]
	v_min_u32_e32 v146, 1, v146
	v_or_b32_e32 v146, v147, v146
	v_cvt_f32_u32_e32 v146, v146
	v_sub_u32_e32 v143, 32, v143
	v_ldexp_f32 v143, v146, v143
	v_fmamk_f32 v143, v143, 0x31800000, v219
	v_cmp_gt_f32_e32 vcc, s86, v143
	v_mul_f32_e32 v146, 0x4b800000, v143
	s_nop 0
	v_cndmask_b32_e32 v143, v143, v146, vcc
	v_rsq_f32_e32 v143, v143
	s_nop 0
	v_mul_f32_e32 v146, 0x45800000, v143
	v_cndmask_b32_e32 v154, v143, v146, vcc
	v_pk_mul_f32 v[126:127], v[126:127], v[154:155] op_sel_hi:[1,0]
	v_pk_mul_f32 v[118:119], v[118:119], v[154:155] op_sel_hi:[1,0]
	v_mul_f32_e32 v143, 0xbfb8aa3b, v126
	v_exp_f32_e32 v143, v143
	v_pk_mul_f32 v[120:121], v[120:121], v[154:155] op_sel_hi:[1,0]
	v_pk_mul_f32 v[122:123], v[122:123], v[154:155] op_sel_hi:[1,0]
	v_pk_mul_f32 v[114:115], v[114:115], v[154:155] op_sel_hi:[1,0]
	v_add_f32_e32 v143, 1.0, v143
	v_rcp_f32_e32 v156, v143
	v_mul_f32_e32 v143, 0xbfb8aa3b, v127
	v_exp_f32_e32 v143, v143
	v_mov_b64_e32 v[146:147], s[8:9]
	v_pk_mul_f32 v[116:117], v[116:117], v[154:155] op_sel_hi:[1,0]
	v_mad_i64_i32 v[150:151], s[22:23], v142, s83, v[146:147]
	v_add_f32_e32 v143, 1.0, v143
	v_rcp_f32_e32 v157, v143
	s_nop 0
	v_pk_mul_f32 v[126:127], v[126:127], v[156:157]
	s_nop 0
	v_pk_mul_f32 v[118:119], v[118:119], v[126:127]
	v_pk_mul_f32 v[126:127], v[128:129], v[154:155] op_sel_hi:[1,0]
	v_cvt_pk_bf16_f32 v118, v118, v119
	v_mul_f32_e32 v128, 0xbfb8aa3b, v126
	v_mul_f32_e32 v129, 0xbfb8aa3b, v127
	v_exp_f32_e32 v128, v128
	v_exp_f32_e32 v129, v129
	v_add_f32_e32 v128, 1.0, v128
	v_add_f32_e32 v129, 1.0, v129
	v_rcp_f32_e32 v128, v128
	v_rcp_f32_e32 v129, v129
	s_nop 0
	v_pk_mul_f32 v[126:127], v[126:127], v[128:129]
	s_nop 0
	v_pk_mul_f32 v[120:121], v[120:121], v[126:127]
	v_mul_f32_e32 v126, 0xbfb8aa3b, v122
	v_mul_f32_e32 v127, 0xbfb8aa3b, v123
	v_exp_f32_e32 v126, v126
	v_exp_f32_e32 v127, v127
	v_cvt_pk_bf16_f32 v119, v120, v121
	v_add_f32_e32 v126, 1.0, v126
	v_add_f32_e32 v127, 1.0, v127
	v_rcp_f32_e32 v126, v126
	v_rcp_f32_e32 v127, v127
	s_nop 0
	v_pk_mul_f32 v[122:123], v[122:123], v[126:127]
	s_nop 0
	v_pk_mul_f32 v[122:123], v[114:115], v[122:123]
	v_pk_mul_f32 v[114:115], v[124:125], v[154:155] op_sel_hi:[1,0]
	v_cvt_pk_bf16_f32 v120, v122, v123
	v_mul_f32_e32 v124, 0xbfb8aa3b, v114
	v_mul_f32_e32 v125, 0xbfb8aa3b, v115
	v_exp_f32_e32 v124, v124
	v_exp_f32_e32 v125, v125
	v_add_f32_e32 v124, 1.0, v124
	v_add_f32_e32 v125, 1.0, v125
	v_rcp_f32_e32 v124, v124
	v_rcp_f32_e32 v125, v125
	s_nop 0
	v_pk_mul_f32 v[114:115], v[114:115], v[124:125]
	s_nop 0
	v_pk_mul_f32 v[116:117], v[116:117], v[114:115]
	v_lshlrev_b64 v[114:115], 1, v[148:149]
	v_lshl_add_u64 v[124:125], v[150:151], 0, v[114:115]
	v_cvt_pk_bf16_f32 v121, v116, v117
	global_store_dwordx4 v[124:125], v[118:121], off
	v_mov_b64_e32 v[116:117], v[158:159]
	s_nop 0
	v_or_b32_e32 v119, 16, v142
	s_nop 0
	v_ffbh_u32_e32 v118, v117
	v_min_u32_e32 v118, 32, v118
	v_lshlrev_b64 v[116:117], v118, v[116:117]
	v_min_u32_e32 v116, 1, v116
	v_or_b32_e32 v116, v117, v116
	v_cvt_f32_u32_e32 v116, v116
	v_sub_u32_e32 v117, 32, v118
	v_ldexp_f32 v116, v116, v117
	v_fmamk_f32 v116, v116, 0x31800000, v219
	v_cmp_gt_f32_e32 vcc, s86, v116
	v_mul_f32_e32 v117, 0x4b800000, v116
	s_nop 0
	v_cndmask_b32_e32 v116, v116, v117, vcc
	v_rsq_f32_e32 v116, v116
	s_nop 0
	v_mul_f32_e32 v117, 0x45800000, v116
	v_cndmask_b32_e32 v118, v116, v117, vcc
	v_pk_mul_f32 v[110:111], v[110:111], v[118:119] op_sel_hi:[1,0]
	v_mad_i64_i32 v[116:117], s[22:23], v119, s83, v[146:147]
	v_mul_f32_e32 v119, 0xbfb8aa3b, v110
	v_exp_f32_e32 v119, v119
	s_nop 0
	v_add_f32_e32 v119, 1.0, v119
	v_rcp_f32_e32 v120, v119
	v_pk_mul_f32 v[102:103], v[102:103], v[118:119] op_sel_hi:[1,0]
	v_mul_f32_e32 v119, 0xbfb8aa3b, v111
	v_exp_f32_e32 v119, v119
	s_nop 0
	v_add_f32_e32 v119, 1.0, v119
	v_rcp_f32_e32 v121, v119
	v_pk_mul_f32 v[104:105], v[104:105], v[118:119] op_sel_hi:[1,0]
	v_pk_mul_f32 v[106:107], v[106:107], v[118:119] op_sel_hi:[1,0]
	v_pk_mul_f32 v[98:99], v[98:99], v[118:119] op_sel_hi:[1,0]
	v_pk_mul_f32 v[110:111], v[110:111], v[120:121]
	v_pk_mul_f32 v[100:101], v[100:101], v[118:119] op_sel_hi:[1,0]
	v_pk_mul_f32 v[102:103], v[102:103], v[110:111]
	v_pk_mul_f32 v[110:111], v[112:113], v[118:119] op_sel_hi:[1,0]
	v_cvt_pk_bf16_f32 v102, v102, v103
	v_mul_f32_e32 v112, 0xbfb8aa3b, v110
	v_mul_f32_e32 v113, 0xbfb8aa3b, v111
	v_exp_f32_e32 v112, v112
	v_exp_f32_e32 v113, v113
	v_add_f32_e32 v112, 1.0, v112
	v_add_f32_e32 v113, 1.0, v113
	v_rcp_f32_e32 v112, v112
	v_rcp_f32_e32 v113, v113
	s_nop 0
	v_pk_mul_f32 v[110:111], v[110:111], v[112:113]
	s_nop 0
	v_pk_mul_f32 v[104:105], v[104:105], v[110:111]
	v_mul_f32_e32 v110, 0xbfb8aa3b, v106
	v_mul_f32_e32 v111, 0xbfb8aa3b, v107
	v_exp_f32_e32 v110, v110
	v_exp_f32_e32 v111, v111
	v_cvt_pk_bf16_f32 v103, v104, v105
	v_add_f32_e32 v110, 1.0, v110
	v_add_f32_e32 v111, 1.0, v111
	v_rcp_f32_e32 v110, v110
	v_rcp_f32_e32 v111, v111
	s_nop 0
	v_pk_mul_f32 v[106:107], v[106:107], v[110:111]
	s_nop 0
	v_pk_mul_f32 v[98:99], v[98:99], v[106:107]
	v_pk_mul_f32 v[106:107], v[108:109], v[118:119] op_sel_hi:[1,0]
	v_cvt_pk_bf16_f32 v104, v98, v99
	v_mul_f32_e32 v108, 0xbfb8aa3b, v106
	v_mul_f32_e32 v109, 0xbfb8aa3b, v107
	v_exp_f32_e32 v108, v108
	v_exp_f32_e32 v109, v109
	v_add_f32_e32 v108, 1.0, v108
	v_add_f32_e32 v109, 1.0, v109
	v_rcp_f32_e32 v108, v108
	v_rcp_f32_e32 v109, v109
	s_nop 0
	v_pk_mul_f32 v[106:107], v[106:107], v[108:109]
	s_nop 0
	v_pk_mul_f32 v[100:101], v[100:101], v[106:107]
	v_lshl_add_u64 v[106:107], v[116:117], 0, v[114:115]
	v_cvt_pk_bf16_f32 v105, v100, v101
	global_store_dwordx4 v[106:107], v[102:105], off
	v_mov_b64_e32 v[98:99], v[160:161]
	v_or_b32_e32 v101, 32, v142
	s_nop 0
	v_ffbh_u32_e32 v100, v99
	v_min_u32_e32 v100, 32, v100
	v_lshlrev_b64 v[98:99], v100, v[98:99]
	v_min_u32_e32 v98, 1, v98
	v_or_b32_e32 v98, v99, v98
	v_cvt_f32_u32_e32 v98, v98
	v_sub_u32_e32 v99, 32, v100
	v_ldexp_f32 v98, v98, v99
	v_fmamk_f32 v98, v98, 0x31800000, v219
	v_cmp_gt_f32_e32 vcc, s86, v98
	v_mul_f32_e32 v99, 0x4b800000, v98
	s_nop 0
	v_cndmask_b32_e32 v98, v98, v99, vcc
	v_rsq_f32_e32 v98, v98
	s_nop 0
	v_mul_f32_e32 v99, 0x45800000, v98
	v_cndmask_b32_e32 v100, v98, v99, vcc
	v_pk_mul_f32 v[94:95], v[94:95], v[100:101] op_sel_hi:[1,0]
	v_mad_i64_i32 v[98:99], s[22:23], v101, s83, v[146:147]
	v_mul_f32_e32 v101, 0xbfb8aa3b, v94
	v_exp_f32_e32 v101, v101
	s_nop 0
	v_add_f32_e32 v101, 1.0, v101
	v_rcp_f32_e32 v102, v101
	v_pk_mul_f32 v[86:87], v[86:87], v[100:101] op_sel_hi:[1,0]
	v_mul_f32_e32 v101, 0xbfb8aa3b, v95
	v_exp_f32_e32 v101, v101
	s_nop 0
	v_add_f32_e32 v101, 1.0, v101
	v_rcp_f32_e32 v103, v101
	v_pk_mul_f32 v[88:89], v[88:89], v[100:101] op_sel_hi:[1,0]
	v_pk_mul_f32 v[90:91], v[90:91], v[100:101] op_sel_hi:[1,0]
	v_pk_mul_f32 v[82:83], v[82:83], v[100:101] op_sel_hi:[1,0]
	v_pk_mul_f32 v[94:95], v[94:95], v[102:103]
	v_pk_mul_f32 v[84:85], v[84:85], v[100:101] op_sel_hi:[1,0]
	v_pk_mul_f32 v[86:87], v[86:87], v[94:95]
	v_pk_mul_f32 v[94:95], v[96:97], v[100:101] op_sel_hi:[1,0]
	v_cvt_pk_bf16_f32 v86, v86, v87
	v_mul_f32_e32 v96, 0xbfb8aa3b, v94
	v_mul_f32_e32 v97, 0xbfb8aa3b, v95
	v_exp_f32_e32 v96, v96
	v_exp_f32_e32 v97, v97
	v_add_f32_e32 v96, 1.0, v96
	v_add_f32_e32 v97, 1.0, v97
	v_rcp_f32_e32 v96, v96
	v_rcp_f32_e32 v97, v97
	s_nop 0
	v_pk_mul_f32 v[94:95], v[94:95], v[96:97]
	s_nop 0
	v_pk_mul_f32 v[88:89], v[88:89], v[94:95]
	v_mul_f32_e32 v94, 0xbfb8aa3b, v90
	v_mul_f32_e32 v95, 0xbfb8aa3b, v91
	v_exp_f32_e32 v94, v94
	v_exp_f32_e32 v95, v95
	v_cvt_pk_bf16_f32 v87, v88, v89
	v_add_f32_e32 v94, 1.0, v94
	v_add_f32_e32 v95, 1.0, v95
	v_rcp_f32_e32 v94, v94
	v_rcp_f32_e32 v95, v95
	s_nop 0
	v_pk_mul_f32 v[90:91], v[90:91], v[94:95]
	s_nop 0
	v_pk_mul_f32 v[82:83], v[82:83], v[90:91]
	v_pk_mul_f32 v[90:91], v[92:93], v[100:101] op_sel_hi:[1,0]
	v_cvt_pk_bf16_f32 v88, v82, v83
	v_mul_f32_e32 v92, 0xbfb8aa3b, v90
	v_mul_f32_e32 v93, 0xbfb8aa3b, v91
	v_exp_f32_e32 v92, v92
	v_exp_f32_e32 v93, v93
	v_add_f32_e32 v92, 1.0, v92
	v_add_f32_e32 v93, 1.0, v93
	v_rcp_f32_e32 v92, v92
	v_rcp_f32_e32 v93, v93
	s_nop 0
	v_pk_mul_f32 v[90:91], v[90:91], v[92:93]
	s_nop 0
	v_pk_mul_f32 v[84:85], v[84:85], v[90:91]
	v_lshl_add_u64 v[90:91], v[98:99], 0, v[114:115]
	v_cvt_pk_bf16_f32 v89, v84, v85
	global_store_dwordx4 v[90:91], v[86:89], off
	v_mov_b64_e32 v[82:83], v[162:163]
	v_or_b32_e32 v85, 48, v142
	s_nop 0
	v_ffbh_u32_e32 v84, v83
	v_min_u32_e32 v84, 32, v84
	v_lshlrev_b64 v[82:83], v84, v[82:83]
	v_min_u32_e32 v82, 1, v82
	v_or_b32_e32 v82, v83, v82
	v_cvt_f32_u32_e32 v82, v82
	v_sub_u32_e32 v83, 32, v84
	v_ldexp_f32 v82, v82, v83
	v_fmamk_f32 v82, v82, 0x31800000, v219
	v_cmp_gt_f32_e32 vcc, s86, v82
	v_mul_f32_e32 v83, 0x4b800000, v82
	s_nop 0
	v_cndmask_b32_e32 v82, v82, v83, vcc
	v_rsq_f32_e32 v82, v82
	s_nop 0
	v_mul_f32_e32 v83, 0x45800000, v82
	v_cndmask_b32_e32 v84, v82, v83, vcc
	v_pk_mul_f32 v[78:79], v[78:79], v[84:85] op_sel_hi:[1,0]
	v_mad_i64_i32 v[82:83], s[22:23], v85, s83, v[146:147]
	v_mul_f32_e32 v85, 0xbfb8aa3b, v78
	v_exp_f32_e32 v85, v85
	s_nop 0
	v_add_f32_e32 v85, 1.0, v85
	v_rcp_f32_e32 v86, v85
	v_pk_mul_f32 v[70:71], v[70:71], v[84:85] op_sel_hi:[1,0]
	v_mul_f32_e32 v85, 0xbfb8aa3b, v79
	v_exp_f32_e32 v85, v85
	s_nop 0
	v_add_f32_e32 v85, 1.0, v85
	v_rcp_f32_e32 v87, v85
	v_pk_mul_f32 v[72:73], v[72:73], v[84:85] op_sel_hi:[1,0]
	v_pk_mul_f32 v[74:75], v[74:75], v[84:85] op_sel_hi:[1,0]
	v_pk_mul_f32 v[66:67], v[66:67], v[84:85] op_sel_hi:[1,0]
	v_pk_mul_f32 v[78:79], v[78:79], v[86:87]
	v_pk_mul_f32 v[68:69], v[68:69], v[84:85] op_sel_hi:[1,0]
	v_pk_mul_f32 v[70:71], v[70:71], v[78:79]
	v_pk_mul_f32 v[78:79], v[80:81], v[84:85] op_sel_hi:[1,0]
	v_cvt_pk_bf16_f32 v70, v70, v71
	v_mul_f32_e32 v80, 0xbfb8aa3b, v78
	v_mul_f32_e32 v81, 0xbfb8aa3b, v79
	v_exp_f32_e32 v80, v80
	v_exp_f32_e32 v81, v81
	v_add_f32_e32 v80, 1.0, v80
	v_add_f32_e32 v81, 1.0, v81
	v_rcp_f32_e32 v80, v80
	v_rcp_f32_e32 v81, v81
	s_nop 0
	v_pk_mul_f32 v[78:79], v[78:79], v[80:81]
	s_nop 0
	v_pk_mul_f32 v[72:73], v[72:73], v[78:79]
	v_mul_f32_e32 v78, 0xbfb8aa3b, v74
	v_mul_f32_e32 v79, 0xbfb8aa3b, v75
	v_exp_f32_e32 v78, v78
	v_exp_f32_e32 v79, v79
	v_cvt_pk_bf16_f32 v71, v72, v73
	v_add_f32_e32 v78, 1.0, v78
	v_add_f32_e32 v79, 1.0, v79
	v_rcp_f32_e32 v78, v78
	v_rcp_f32_e32 v79, v79
	s_nop 0
	v_pk_mul_f32 v[74:75], v[74:75], v[78:79]
	s_nop 0
	v_pk_mul_f32 v[66:67], v[66:67], v[74:75]
	v_pk_mul_f32 v[74:75], v[76:77], v[84:85] op_sel_hi:[1,0]
	v_cvt_pk_bf16_f32 v72, v66, v67
	v_mul_f32_e32 v76, 0xbfb8aa3b, v74
	v_mul_f32_e32 v77, 0xbfb8aa3b, v75
	v_exp_f32_e32 v76, v76
	v_exp_f32_e32 v77, v77
	v_add_f32_e32 v76, 1.0, v76
	v_add_f32_e32 v77, 1.0, v77
	v_rcp_f32_e32 v76, v76
	v_rcp_f32_e32 v77, v77
	s_nop 0
	v_pk_mul_f32 v[74:75], v[74:75], v[76:77]
	s_nop 0
	v_pk_mul_f32 v[68:69], v[68:69], v[74:75]
	v_lshl_add_u64 v[74:75], v[82:83], 0, v[114:115]
	v_cvt_pk_bf16_f32 v73, v68, v69
	global_store_dwordx4 v[74:75], v[70:73], off
	v_mov_b64_e32 v[66:67], v[164:165]
	v_add_u32_e32 v69, 0x80, v142
	s_nop 0
	v_ffbh_u32_e32 v68, v67
	v_min_u32_e32 v68, 32, v68
	v_lshlrev_b64 v[66:67], v68, v[66:67]
	v_min_u32_e32 v66, 1, v66
	v_or_b32_e32 v66, v67, v66
	v_cvt_f32_u32_e32 v66, v66
	v_sub_u32_e32 v67, 32, v68
	v_ldexp_f32 v66, v66, v67
	v_fmamk_f32 v66, v66, 0x31800000, v219
	v_cmp_gt_f32_e32 vcc, s86, v66
	v_mul_f32_e32 v67, 0x4b800000, v66
	s_nop 0
	v_cndmask_b32_e32 v66, v66, v67, vcc
	v_rsq_f32_e32 v66, v66
	s_nop 0
	v_mul_f32_e32 v67, 0x45800000, v66
	v_cndmask_b32_e32 v68, v66, v67, vcc
	v_pk_mul_f32 v[62:63], v[62:63], v[68:69] op_sel_hi:[1,0]
	v_mad_i64_i32 v[66:67], s[22:23], v69, s83, v[146:147]
	v_mul_f32_e32 v69, 0xbfb8aa3b, v62
	v_exp_f32_e32 v69, v69
	s_nop 0
	v_add_f32_e32 v69, 1.0, v69
	v_rcp_f32_e32 v70, v69
	v_pk_mul_f32 v[54:55], v[54:55], v[68:69] op_sel_hi:[1,0]
	v_mul_f32_e32 v69, 0xbfb8aa3b, v63
	v_exp_f32_e32 v69, v69
	s_nop 0
	v_add_f32_e32 v69, 1.0, v69
	v_rcp_f32_e32 v71, v69
	v_pk_mul_f32 v[56:57], v[56:57], v[68:69] op_sel_hi:[1,0]
	v_pk_mul_f32 v[58:59], v[58:59], v[68:69] op_sel_hi:[1,0]
	v_pk_mul_f32 v[50:51], v[50:51], v[68:69] op_sel_hi:[1,0]
	v_pk_mul_f32 v[62:63], v[62:63], v[70:71]
	v_pk_mul_f32 v[52:53], v[52:53], v[68:69] op_sel_hi:[1,0]
	v_pk_mul_f32 v[54:55], v[54:55], v[62:63]
	v_pk_mul_f32 v[62:63], v[64:65], v[68:69] op_sel_hi:[1,0]
	v_cvt_pk_bf16_f32 v54, v54, v55
	v_mul_f32_e32 v64, 0xbfb8aa3b, v62
	v_mul_f32_e32 v65, 0xbfb8aa3b, v63
	v_exp_f32_e32 v64, v64
	v_exp_f32_e32 v65, v65
	v_add_f32_e32 v64, 1.0, v64
	v_add_f32_e32 v65, 1.0, v65
	v_rcp_f32_e32 v64, v64
	v_rcp_f32_e32 v65, v65
	s_nop 0
	v_pk_mul_f32 v[62:63], v[62:63], v[64:65]
	s_nop 0
	v_pk_mul_f32 v[56:57], v[56:57], v[62:63]
	v_mul_f32_e32 v62, 0xbfb8aa3b, v58
	v_mul_f32_e32 v63, 0xbfb8aa3b, v59
	v_exp_f32_e32 v62, v62
	v_exp_f32_e32 v63, v63
	v_cvt_pk_bf16_f32 v55, v56, v57
	v_add_f32_e32 v62, 1.0, v62
	v_add_f32_e32 v63, 1.0, v63
	v_rcp_f32_e32 v62, v62
	v_rcp_f32_e32 v63, v63
	s_nop 0
	v_pk_mul_f32 v[58:59], v[58:59], v[62:63]
	s_nop 0
	v_pk_mul_f32 v[50:51], v[50:51], v[58:59]
	v_pk_mul_f32 v[58:59], v[60:61], v[68:69] op_sel_hi:[1,0]
	v_cvt_pk_bf16_f32 v56, v50, v51
	v_mul_f32_e32 v60, 0xbfb8aa3b, v58
	v_mul_f32_e32 v61, 0xbfb8aa3b, v59
	v_exp_f32_e32 v60, v60
	v_exp_f32_e32 v61, v61
	v_add_f32_e32 v60, 1.0, v60
	v_add_f32_e32 v61, 1.0, v61
	v_rcp_f32_e32 v60, v60
	v_rcp_f32_e32 v61, v61
	s_nop 0
	v_pk_mul_f32 v[58:59], v[58:59], v[60:61]
	s_nop 0
	v_pk_mul_f32 v[52:53], v[52:53], v[58:59]
	v_lshl_add_u64 v[58:59], v[66:67], 0, v[114:115]
	v_cvt_pk_bf16_f32 v57, v52, v53
	global_store_dwordx4 v[58:59], v[54:57], off
	v_mov_b64_e32 v[50:51], v[166:167]
	v_add_u32_e32 v53, 0x90, v142
	s_nop 0
	v_ffbh_u32_e32 v52, v51
	v_min_u32_e32 v52, 32, v52
	v_lshlrev_b64 v[50:51], v52, v[50:51]
	v_min_u32_e32 v50, 1, v50
	v_or_b32_e32 v50, v51, v50
	v_cvt_f32_u32_e32 v50, v50
	v_sub_u32_e32 v51, 32, v52
	v_ldexp_f32 v50, v50, v51
	v_fmamk_f32 v50, v50, 0x31800000, v219
	v_cmp_gt_f32_e32 vcc, s86, v50
	v_mul_f32_e32 v51, 0x4b800000, v50
	s_nop 0
	v_cndmask_b32_e32 v50, v50, v51, vcc
	v_rsq_f32_e32 v50, v50
	s_nop 0
	v_mul_f32_e32 v51, 0x45800000, v50
	v_cndmask_b32_e32 v52, v50, v51, vcc
	v_pk_mul_f32 v[46:47], v[46:47], v[52:53] op_sel_hi:[1,0]
	v_mad_i64_i32 v[50:51], s[22:23], v53, s83, v[146:147]
	v_mul_f32_e32 v53, 0xbfb8aa3b, v46
	v_exp_f32_e32 v53, v53
	s_nop 0
	v_add_f32_e32 v53, 1.0, v53
	v_rcp_f32_e32 v54, v53
	v_pk_mul_f32 v[38:39], v[38:39], v[52:53] op_sel_hi:[1,0]
	v_mul_f32_e32 v53, 0xbfb8aa3b, v47
	v_exp_f32_e32 v53, v53
	s_nop 0
	v_add_f32_e32 v53, 1.0, v53
	v_rcp_f32_e32 v55, v53
	v_pk_mul_f32 v[40:41], v[40:41], v[52:53] op_sel_hi:[1,0]
	v_pk_mul_f32 v[42:43], v[42:43], v[52:53] op_sel_hi:[1,0]
	v_pk_mul_f32 v[34:35], v[34:35], v[52:53] op_sel_hi:[1,0]
	v_pk_mul_f32 v[46:47], v[46:47], v[54:55]
	v_pk_mul_f32 v[36:37], v[36:37], v[52:53] op_sel_hi:[1,0]
	v_pk_mul_f32 v[38:39], v[38:39], v[46:47]
	v_pk_mul_f32 v[46:47], v[48:49], v[52:53] op_sel_hi:[1,0]
	v_cvt_pk_bf16_f32 v38, v38, v39
	v_mul_f32_e32 v48, 0xbfb8aa3b, v46
	v_mul_f32_e32 v49, 0xbfb8aa3b, v47
	v_exp_f32_e32 v48, v48
	v_exp_f32_e32 v49, v49
	v_add_f32_e32 v48, 1.0, v48
	v_add_f32_e32 v49, 1.0, v49
	v_rcp_f32_e32 v48, v48
	v_rcp_f32_e32 v49, v49
	s_nop 0
	v_pk_mul_f32 v[46:47], v[46:47], v[48:49]
	s_nop 0
	v_pk_mul_f32 v[40:41], v[40:41], v[46:47]
	v_mul_f32_e32 v46, 0xbfb8aa3b, v42
	v_mul_f32_e32 v47, 0xbfb8aa3b, v43
	v_exp_f32_e32 v46, v46
	v_exp_f32_e32 v47, v47
	v_cvt_pk_bf16_f32 v39, v40, v41
	v_add_f32_e32 v46, 1.0, v46
	v_add_f32_e32 v47, 1.0, v47
	v_rcp_f32_e32 v46, v46
	v_rcp_f32_e32 v47, v47
	s_nop 0
	v_pk_mul_f32 v[42:43], v[42:43], v[46:47]
	s_nop 0
	v_pk_mul_f32 v[34:35], v[34:35], v[42:43]
	v_pk_mul_f32 v[42:43], v[44:45], v[52:53] op_sel_hi:[1,0]
	v_cvt_pk_bf16_f32 v40, v34, v35
	v_mul_f32_e32 v44, 0xbfb8aa3b, v42
	v_mul_f32_e32 v45, 0xbfb8aa3b, v43
	v_exp_f32_e32 v44, v44
	v_exp_f32_e32 v45, v45
	v_add_f32_e32 v44, 1.0, v44
	v_add_f32_e32 v45, 1.0, v45
	v_rcp_f32_e32 v44, v44
	v_rcp_f32_e32 v45, v45
	s_nop 0
	v_pk_mul_f32 v[42:43], v[42:43], v[44:45]
	s_nop 0
	v_pk_mul_f32 v[36:37], v[36:37], v[42:43]
	v_lshl_add_u64 v[42:43], v[50:51], 0, v[114:115]
	v_cvt_pk_bf16_f32 v41, v36, v37
	global_store_dwordx4 v[42:43], v[38:41], off
	v_mov_b64_e32 v[34:35], v[168:169]
	v_add_u32_e32 v37, 0xa0, v142
	s_nop 0
	v_ffbh_u32_e32 v36, v35
	v_min_u32_e32 v36, 32, v36
	v_lshlrev_b64 v[34:35], v36, v[34:35]
	v_min_u32_e32 v34, 1, v34
	v_or_b32_e32 v34, v35, v34
	v_cvt_f32_u32_e32 v34, v34
	v_sub_u32_e32 v35, 32, v36
	v_ldexp_f32 v34, v34, v35
	v_fmamk_f32 v34, v34, 0x31800000, v219
	v_cmp_gt_f32_e32 vcc, s86, v34
	v_mul_f32_e32 v35, 0x4b800000, v34
	s_nop 0
	v_cndmask_b32_e32 v34, v34, v35, vcc
	v_rsq_f32_e32 v34, v34
	s_nop 0
	v_mul_f32_e32 v35, 0x45800000, v34
	v_cndmask_b32_e32 v36, v34, v35, vcc
	v_pk_mul_f32 v[30:31], v[30:31], v[36:37] op_sel_hi:[1,0]
	v_mad_i64_i32 v[34:35], s[22:23], v37, s83, v[146:147]
	v_mul_f32_e32 v37, 0xbfb8aa3b, v30
	v_exp_f32_e32 v37, v37
	s_nop 0
	v_add_f32_e32 v37, 1.0, v37
	v_rcp_f32_e32 v38, v37
	v_pk_mul_f32 v[22:23], v[22:23], v[36:37] op_sel_hi:[1,0]
	v_mul_f32_e32 v37, 0xbfb8aa3b, v31
	v_exp_f32_e32 v37, v37
	s_nop 0
	v_add_f32_e32 v37, 1.0, v37
	v_rcp_f32_e32 v39, v37
	v_pk_mul_f32 v[24:25], v[24:25], v[36:37] op_sel_hi:[1,0]
	v_pk_mul_f32 v[26:27], v[26:27], v[36:37] op_sel_hi:[1,0]
	v_pk_mul_f32 v[18:19], v[18:19], v[36:37] op_sel_hi:[1,0]
	v_pk_mul_f32 v[30:31], v[30:31], v[38:39]
	v_pk_mul_f32 v[20:21], v[20:21], v[36:37] op_sel_hi:[1,0]
	v_pk_mul_f32 v[22:23], v[22:23], v[30:31]
	v_pk_mul_f32 v[30:31], v[32:33], v[36:37] op_sel_hi:[1,0]
	v_cvt_pk_bf16_f32 v22, v22, v23
	v_mul_f32_e32 v32, 0xbfb8aa3b, v30
	v_mul_f32_e32 v33, 0xbfb8aa3b, v31
	v_exp_f32_e32 v32, v32
	v_exp_f32_e32 v33, v33
	v_add_f32_e32 v32, 1.0, v32
	v_add_f32_e32 v33, 1.0, v33
	v_rcp_f32_e32 v32, v32
	v_rcp_f32_e32 v33, v33
	s_nop 0
	v_pk_mul_f32 v[30:31], v[30:31], v[32:33]
	s_nop 0
	v_pk_mul_f32 v[24:25], v[24:25], v[30:31]
	v_mul_f32_e32 v30, 0xbfb8aa3b, v26
	v_mul_f32_e32 v31, 0xbfb8aa3b, v27
	v_exp_f32_e32 v30, v30
	v_exp_f32_e32 v31, v31
	v_cvt_pk_bf16_f32 v23, v24, v25
	v_add_f32_e32 v30, 1.0, v30
	v_add_f32_e32 v31, 1.0, v31
	v_rcp_f32_e32 v30, v30
	v_rcp_f32_e32 v31, v31
	s_nop 0
	v_pk_mul_f32 v[26:27], v[26:27], v[30:31]
	s_nop 0
	v_pk_mul_f32 v[18:19], v[18:19], v[26:27]
	v_pk_mul_f32 v[26:27], v[28:29], v[36:37] op_sel_hi:[1,0]
	v_cvt_pk_bf16_f32 v24, v18, v19
	v_mul_f32_e32 v28, 0xbfb8aa3b, v26
	v_mul_f32_e32 v29, 0xbfb8aa3b, v27
	v_exp_f32_e32 v28, v28
	v_exp_f32_e32 v29, v29
	v_add_f32_e32 v28, 1.0, v28
	v_add_f32_e32 v29, 1.0, v29
	v_rcp_f32_e32 v28, v28
	v_rcp_f32_e32 v29, v29
	s_nop 0
	v_pk_mul_f32 v[26:27], v[26:27], v[28:29]
	s_nop 0
	v_pk_mul_f32 v[20:21], v[20:21], v[26:27]
	v_lshl_add_u64 v[26:27], v[34:35], 0, v[114:115]
	v_cvt_pk_bf16_f32 v25, v20, v21
	global_store_dwordx4 v[26:27], v[22:25], off
	v_mov_b64_e32 v[18:19], v[170:171]
	v_add_u32_e32 v20, 0xb0, v142
	s_nop 0
	v_ffbh_u32_e32 v21, v19
	v_min_u32_e32 v21, 32, v21
	v_lshlrev_b64 v[18:19], v21, v[18:19]
	v_min_u32_e32 v18, 1, v18
	v_or_b32_e32 v18, v19, v18
	v_cvt_f32_u32_e32 v18, v18
	v_sub_u32_e32 v19, 32, v21
	v_mad_i64_i32 v[20:21], s[22:23], v20, s83, v[146:147]
	v_ldexp_f32 v18, v18, v19
	v_fmamk_f32 v18, v18, 0x31800000, v219
	v_cmp_gt_f32_e32 vcc, s86, v18
	v_mul_f32_e32 v19, 0x4b800000, v18
	s_mov_b64 s[22:23], -1
	v_cndmask_b32_e32 v18, v18, v19, vcc
	v_rsq_f32_e32 v18, v18
	s_nop 0
	v_mul_f32_e32 v19, 0x45800000, v18
	v_cndmask_b32_e32 v18, v18, v19, vcc
	v_pk_mul_f32 v[14:15], v[14:15], v[18:19] op_sel_hi:[1,0]
	s_andn2_b64 vcc, exec, s[2:3]
	v_mul_f32_e32 v19, 0xbfb8aa3b, v14
	v_exp_f32_e32 v19, v19
	s_nop 0
	v_add_f32_e32 v19, 1.0, v19
	v_rcp_f32_e32 v22, v19
	v_pk_mul_f32 v[6:7], v[6:7], v[18:19] op_sel_hi:[1,0]
	v_mul_f32_e32 v19, 0xbfb8aa3b, v15
	v_exp_f32_e32 v19, v19
	s_nop 0
	v_add_f32_e32 v19, 1.0, v19
	v_rcp_f32_e32 v23, v19
	v_pk_mul_f32 v[8:9], v[8:9], v[18:19] op_sel_hi:[1,0]
	v_pk_mul_f32 v[10:11], v[10:11], v[18:19] op_sel_hi:[1,0]
	v_pk_mul_f32 v[2:3], v[2:3], v[18:19] op_sel_hi:[1,0]
	v_pk_mul_f32 v[14:15], v[14:15], v[22:23]
	v_pk_mul_f32 v[4:5], v[4:5], v[18:19] op_sel_hi:[1,0]
	v_pk_mul_f32 v[6:7], v[6:7], v[14:15]
	v_pk_mul_f32 v[14:15], v[16:17], v[18:19] op_sel_hi:[1,0]
	s_nop 0
	v_mul_f32_e32 v16, 0xbfb8aa3b, v14
	v_mul_f32_e32 v17, 0xbfb8aa3b, v15
	v_exp_f32_e32 v16, v16
	v_exp_f32_e32 v17, v17
	v_add_f32_e32 v16, 1.0, v16
	v_add_f32_e32 v17, 1.0, v17
	v_rcp_f32_e32 v16, v16
	v_rcp_f32_e32 v17, v17
	s_nop 0
	v_pk_mul_f32 v[14:15], v[14:15], v[16:17]
	s_nop 0
	v_pk_mul_f32 v[8:9], v[8:9], v[14:15]
	v_mul_f32_e32 v14, 0xbfb8aa3b, v10
	v_mul_f32_e32 v15, 0xbfb8aa3b, v11
	v_exp_f32_e32 v14, v14
	v_exp_f32_e32 v15, v15
	v_add_f32_e32 v14, 1.0, v14
	v_add_f32_e32 v15, 1.0, v15
	v_rcp_f32_e32 v14, v14
	v_rcp_f32_e32 v15, v15
	s_nop 0
	v_pk_mul_f32 v[10:11], v[10:11], v[14:15]
	s_nop 0
	v_pk_mul_f32 v[10:11], v[2:3], v[10:11]
	v_pk_mul_f32 v[2:3], v[12:13], v[18:19] op_sel_hi:[1,0]
	v_lshl_add_u64 v[14:15], v[20:21], 0, v[114:115]
	v_mul_f32_e32 v12, 0xbfb8aa3b, v2
	v_mul_f32_e32 v13, 0xbfb8aa3b, v3
	v_exp_f32_e32 v12, v12
	v_exp_f32_e32 v13, v13
	v_add_f32_e32 v12, 1.0, v12
	v_add_f32_e32 v13, 1.0, v13
	v_rcp_f32_e32 v12, v12
	v_rcp_f32_e32 v13, v13
	s_nop 0
	v_pk_mul_f32 v[2:3], v[2:3], v[12:13]
	s_nop 0
	v_pk_mul_f32 v[12:13], v[4:5], v[2:3]
	v_cvt_pk_bf16_f32 v2, v6, v7
	v_cvt_pk_bf16_f32 v3, v8, v9
	v_cvt_pk_bf16_f32 v4, v10, v11
	v_cvt_pk_bf16_f32 v5, v12, v13
	global_store_dwordx4 v[14:15], v[2:5], off
	s_cbranch_vccnz .LBB0_1176
	s_andn2_b64 vcc, exec, s[6:7]
	s_cbranch_vccnz .LBB0_1175
	s_barrier
	s_branch .LBB0_1175

.LBB0_1236:
	s_or_b64 exec, exec, s[4:5]
	s_mov_b64 s[4:5], exec
	v_mbcnt_lo_u32_b32 v1, s4, 0
	v_mbcnt_hi_u32_b32 v1, s5, v1
	v_cmp_eq_u32_e32 vcc, 0, v1
	s_and_saveexec_b64 s[10:11], vcc
	s_cbranch_execz .LBB0_1238
	s_bcnt1_i32_b64 s4, s[4:5]
	v_mov_b32_e32 v1, s4
	global_atomic_add v254, v1, s[6:7] offset:1024

.LBB0_1335:
	s_or_b64 exec, exec, s[6:7]
	s_mov_b64 s[6:7], exec
	v_mbcnt_lo_u32_b32 v1, s6, 0
	v_mbcnt_hi_u32_b32 v1, s7, v1
	v_cmp_eq_u32_e32 vcc, 0, v1
	s_and_saveexec_b64 s[8:9], vcc
	s_cbranch_execnz .LBB0_1336
	s_getpc_b64 s[98:99]
